# M1b attention hand-rewritten: transposed scores, in-register P, V via ds_read_b64_tr_b16, 8B stores
# speedup vs baseline: 1.0175x; 1.0175x over previous
; __global__ void __launch_bounds__(512, 2) fwd_megakernel(Args args) {
;     ...
;                 const int nb = unit & 31, b = unit >> 5;
;                 const size_t grow0 = (size_t)b * SEQ + nb * 128;
;                 LAS bf16* Ks = (LAS bf16*)lds; LAS bf16* VT = (LAS bf16*)(lds + 36864); LAS bf16* Ps = (LAS bf16*)(lds + 72704) + wave * (16 * 168);
;                 LAS float* s_bias = (LAS float*)(lds + 115712);
;                 s_bias[tid] = args.in[14][T5_BUCKET[tid & 127] * 4 + (tid >> 7)];
;                 for (int it = tid; it < 64 * 24; it += 512) { const int d = it / 24, j = 256 + it % 24; VT[d * 280 + j] = 0; }
;                 f32x4 og[4][4]; float ssr[4] = {0.f, 0.f, 0.f, 0.f};
; #pragma unroll
;                 for (int kvh = 0; kvh < 2; ++kvh) {
;                     if (kvh) __syncthreads();
;                     {
;                         u32x4 kq[4], vq[4];
; #pragma unroll
;                         for (int k = 0; k < 4; ++k) {
;                             const int it = tid + 512 * k, j = it >> 3, d8 = (it & 7) * 8;
;                             kq[k] = (u32x4){0u, 0u, 0u, 0u}; vq[k] = (u32x4){0u, 0u, 0u, 0u};
;                             if (nb > 0 || j >= 128) { const bf16* src = proj + (grow0 + j - 128) * NPROJ + kvh * 64 + d8; kq[k] = *(const u32x4*)(src + PC_K); vq[k] = *(const u32x4*)(src + PC_V); }
;                         }
; #pragma unroll
;                         for (int k = 0; k < 4; ++k) {
;                             const int it = tid + 512 * k, j = it >> 3, d8 = (it & 7) * 8;
;                             *(LAS u32x4*)(Ks + j * 72 + d8) = kq[k];
;                             const unsigned vw[4] = {vq[k].x, vq[k].y, vq[k].z, vq[k].w};
; #pragma unroll
;                             for (int i = 0; i < 4; ++i) { VT[(d8 + 2 * i) * 280 + j] = (bf16)(vw[i] & 0xffffu); VT[(d8 + 2 * i + 1) * 280 + j] = (bf16)(vw[i] >> 16); }
;                         }
;                     }
;                     __syncthreads();
; #pragma unroll
;                     for (int g = 0; g < 2; ++g) {
;                         const int hq = kvh * 2 + g;
;                         const float sink = args.in[13][layer * 4 + hq];
;                         const bf16* qp = proj + (grow0 + 16 * wave + r16) * NPROJ + PC_Q + hq * 64 + q4 * 8;
;                         const bf16x8 aq0 = *(const bf16x8*)qp, aq1 = *(const bf16x8*)(qp + 32);
.LBB0_448:
	s_waitcnt vmcnt(0) lgkmcnt(0)
	v_readlane_b32 s3, v252, 0
	s_mov_b32 s50, 0x3e000000
	s_and_b32 s28, s2, 31
	s_sub_i32 s29, 8, s3
	s_cmp_eq_u32 s28, 0
	s_cselect_b32 s29, s29, 0
	s_mul_i32 s30, s2, 0xb0000
	s_add_u32 s8, s80, 0x15000000
	s_addc_u32 s9, s81, 0
	s_add_u32 s8, s8, s30
	s_addc_u32 s9, s9, 0
	s_lshl_b32 s30, s2, 18
	s_add_u32 s10, s80, 0xa000400
	s_addc_u32 s11, s81, 0
	s_add_u32 s10, s10, s30
	s_addc_u32 s11, s11, 0
	s_lshl_b32 s30, s2, 9
	s_add_u32 s12, s80, 0x400000
	s_addc_u32 s13, s81, 0
	s_add_u32 s12, s12, s30
	s_addc_u32 s13, s13, 0
	v_readlane_b32 s14, v251, 35
	v_readlane_b32 s15, v251, 36
	v_readlane_b32 s30, v253, 58
	s_lshl_b32 s30, s30, 1
	s_add_u32 s14, s14, s30
	s_addc_u32 s15, s15, 0
	s_load_dwordx4 s[36:39], s[14:15], 0x0
	v_readlane_b32 s16, v251, 37
	v_readlane_b32 s17, v251, 38
	s_sub_u32 s18, s8, 0xaf200
	s_subb_u32 s19, s9, 0
	s_add_u32 s20, s18, 0x58000
	s_addc_u32 s21, s19, 0
	s_add_u32 s22, s20, 0x58000
	s_addc_u32 s23, s21, 0
	s_add_u32 s24, s22, 0x58000
	s_addc_u32 s25, s23, 0
	v_and_b32_e32 v160, 15, v195
	v_bfe_u32 v161, v195, 4, 2
	v_lshl_add_u32 v175, s3, 4, v160
	v_mul_u32_u24_e32 v162, 0x90, v175
	v_lshl_add_u32 v162, v161, 4, v162
	v_and_b32_e32 v176, 63, v195
	v_bfe_u32 v177, v176, 2, 2
	v_and_b32_e32 v178, 3, v176
	v_lshl_add_u32 v177, v161, 2, v177
	v_lshl_add_u32 v177, s3, 4, v177
	v_mul_u32_u24_e32 v163, 0x90, v177
	v_lshl_add_u32 v163, v178, 3, v163
	v_add_u32_e32 v163, 0x9000, v163
	v_lshlrev_b32_e32 v164, 2, v160
	v_lshlrev_b32_e32 v177, 4, v161
	v_sub_u32_e32 v164, v164, v177
	v_add_u32_e32 v164, 0x128f4, v164
	v_lshlrev_b32_e32 v165, 11, v175
	v_lshl_add_u32 v165, v161, 3, v165
	v_lshlrev_b32_e32 v166, 2, v175
	v_lshrrev_b32_e32 v177, 3, v195
	v_and_b32_e32 v178, 7, v195
	v_mul_u32_u24_e32 v167, 0x1600, v177
	v_lshl_add_u32 v167, v178, 4, v167
	v_mul_u32_u24_e32 v168, 0x90, v177
	v_lshl_add_u32 v168, v178, 4, v168
	v_mul_u32_u24_e32 v169, 0x1600, v175
	v_lshl_add_u32 v169, v161, 4, v169
	v_add_u32_e32 v169, 0xc00, v169
	v_xor_b32_e32 v173, 16, v176
	v_lshlrev_b32_e32 v173, 2, v173
	v_xor_b32_e32 v174, 32, v176
	v_lshlrev_b32_e32 v174, 2, v174
	v_lshlrev_b32_e32 v177, 2, v161
	v_add_u32_e32 v178, 0, v177
	v_cmp_le_u32_e64 s[40:41], v178, v160
	v_add_u32_e32 v178, 1, v177
	v_cmp_le_u32_e64 s[42:43], v178, v160
	v_add_u32_e32 v178, 2, v177
	v_cmp_le_u32_e64 s[44:45], v178, v160
	v_add_u32_e32 v178, 3, v177
	v_cmp_le_u32_e64 s[46:47], v178, v160
	v_cmp_eq_u32_e64 s[48:49], 0, v161
	s_getpc_b64 s[4:5]
	s_add_u32 s4, s4, _ZL9T5_BUCKET@rel32@lo+4
	s_addc_u32 s5, s5, _ZL9T5_BUCKET@rel32@hi+12
	v_and_b32_e32 v177, 0x7f, v195
	global_load_ubyte v179, v177, s[4:5]
	global_load_dwordx4 v[0:3], v169, s[8:9] offset:0
	global_load_dwordx4 v[4:7], v169, s[8:9] offset:64
	global_load_dwordx4 v[8:11], v169, s[8:9] offset:128
	global_load_dwordx4 v[12:15], v169, s[8:9] offset:192
	global_load_dwordx4 v[16:19], v169, s[8:9] offset:256
	global_load_dwordx4 v[20:23], v169, s[8:9] offset:320
	global_load_dwordx4 v[24:27], v169, s[8:9] offset:384
	global_load_dwordx4 v[28:31], v169, s[8:9] offset:448
	v_mov_b32_e32 v180, 0
	v_mov_b32_e32 v181, 0
	v_mov_b32_e32 v182, 0
	v_mov_b32_e32 v183, 0
	s_movk_i32 s30, 0x90
	v_cmp_gt_u32_e64 s[6:7], s30, v195
	v_lshlrev_b32_e32 v177, 4, v195
	v_add_u32_e32 v177, 73728, v177
	s_and_saveexec_b64 s[34:35], s[6:7]
	ds_write_b128 v177, v[180:183]
	s_mov_b64 exec, s[34:35]
	s_cmp_eq_u32 s28, 0
	s_cbranch_scc1 .Lm1b_st0_first
	global_load_dwordx4 v[120:123], v167, s[18:19] offset:0
	global_load_dwordx4 v[124:127], v167, s[18:19] offset:256
	global_load_dwordx4 v[128:131], v167, s[20:21] offset:0
	global_load_dwordx4 v[132:135], v167, s[20:21] offset:256
	global_load_dwordx4 v[136:139], v167, s[22:23] offset:0
	global_load_dwordx4 v[140:143], v167, s[22:23] offset:256
	global_load_dwordx4 v[144:147], v167, s[24:25] offset:0
	global_load_dwordx4 v[148:151], v167, s[24:25] offset:256
	s_branch .Lm1b_st0_ld
.Lm1b_st0_first:
	v_mov_b32_e32 v120, 0
	v_mov_b32_e32 v121, 0
	v_mov_b32_e32 v122, 0
	v_mov_b32_e32 v123, 0
	v_mov_b32_e32 v124, 0
	v_mov_b32_e32 v125, 0
	v_mov_b32_e32 v126, 0
	v_mov_b32_e32 v127, 0
	v_mov_b32_e32 v128, 0
	v_mov_b32_e32 v129, 0
	v_mov_b32_e32 v130, 0
	v_mov_b32_e32 v131, 0
	v_mov_b32_e32 v132, 0
	v_mov_b32_e32 v133, 0
	v_mov_b32_e32 v134, 0
	v_mov_b32_e32 v135, 0
	global_load_dwordx4 v[136:139], v167, s[22:23] offset:0
	global_load_dwordx4 v[140:143], v167, s[22:23] offset:256
	global_load_dwordx4 v[144:147], v167, s[24:25] offset:0
	global_load_dwordx4 v[148:151], v167, s[24:25] offset:256
; #define LAS __attribute__((address_space(3)))
; __global__ void __launch_bounds__(512, 2) fwd_megakernel(Args args) {
;     ...
; #pragma unroll
;                         for (int k = 0; k < 4; ++k) {
;                             const int it = tid + 512 * k, j = it >> 3, d8 = (it & 7) * 8;
;                             *(LAS u32x4*)(Ks + j * 72 + d8) = kq[k];
;                             const unsigned vw[4] = {vq[k].x, vq[k].y, vq[k].z, vq[k].w};
; #pragma unroll
;                             for (int i = 0; i < 4; ++i) { VT[(d8 + 2 * i) * 280 + j] = (bf16)(vw[i] & 0xffffu); VT[(d8 + 2 * i + 1) * 280 + j] = (bf16)(vw[i] >> 16); }
;                         }
;                     }
;                     __syncthreads();
; #pragma unroll
;                     for (int g = 0; g < 2; ++g) {
;                         const int hq = kvh * 2 + g;
;                         const float sink = args.in[13][layer * 4 + hq];
;                         const bf16* qp = proj + (grow0 + 16 * wave + r16) * NPROJ + PC_Q + hq * 64 + q4 * 8;
;                         const bf16x8 aq0 = *(const bf16x8*)qp, aq1 = *(const bf16x8*)(qp + 32);
;                         f32x4 sc[9];
; #pragma unroll
;                         for (int kk = 0; kk < 9; ++kk) {
;                             const int krow = 16 * (wave + kk) + r16;
;                             f32x4 a = (f32x4){0.f, 0.f, 0.f, 0.f};
;                             a = mfma16(aq0, lds_frag(Ks, krow, 72, q4 * 8), a);
;                             a = mfma16(aq1, lds_frag(Ks, krow, 72, 32 + q4 * 8), a);
;                             sc[kk] = a;
;                         }
;                         float sm[4];
; #pragma unroll
;                         for (int j = 0; j < 4; ++j) {
;                             const int i = 16 * wave + q4 * 4 + j; float m = -INFINITY;
; #pragma unroll
;                             for (int kk = 0; kk < 9; ++kk) {
;                                 const int jk = 16 * (wave + kk) + r16, dist = i - jk + 128;
;                                 const bool ok = (dist >= 0) && (dist < 128) && (nb > 0 || jk >= 128);
;                                 const float sv = ok ? sc[kk][j] * 0.125f + s_bias[hq * 128 + (dist & 127)] : -INFINITY;
;                                 sc[kk][j] = sv; m = fmaxf(m, sv);
;                             }
.Lm1b_st0_ld:
	s_waitcnt vmcnt(0)
	ds_write_b128 v168, v[120:123] offset:0
	ds_write_b128 v168, v[124:127] offset:36864
	ds_write_b128 v168, v[128:131] offset:9216
	ds_write_b128 v168, v[132:135] offset:46080
	ds_write_b128 v168, v[136:139] offset:18432
	ds_write_b128 v168, v[140:143] offset:55296
	ds_write_b128 v168, v[144:147] offset:27648
	ds_write_b128 v168, v[148:151] offset:64512
	v_lshrrev_b32_e32 v177, 7, v195
	v_lshl_add_u32 v177, v179, 2, v177
	v_lshlrev_b32_e32 v177, 2, v177
	global_load_dword v179, v177, s[16:17]
	v_lshlrev_b32_e32 v178, 2, v195
	v_add_u32_e32 v178, 76032, v178
	s_waitcnt vmcnt(0)
	ds_write_b32 v178, v179
	s_waitcnt lgkmcnt(0)
	s_barrier
	v_mov_b32_e32 v179, 0x3fb8aa3b
	v_add_u32_e32 v175, 0, v164
	ds_read_b128 v[104:107], v162 offset:0
	ds_read_b128 v[108:111], v162 offset:64
	ds_read_b128 v[112:115], v162 offset:2304
	ds_read_b128 v[116:119], v162 offset:2368
	s_waitcnt lgkmcnt(2)
	v_mfma_f32_16x16x32_bf16 v[32:35], v[104:107], v[0:3], 0
	v_mfma_f32_16x16x32_bf16 v[32:35], v[108:111], v[4:7], v[32:35]
	ds_read_b128 v[104:107], v162 offset:4608
	ds_read_b128 v[108:111], v162 offset:4672
	s_waitcnt lgkmcnt(2)
	v_mfma_f32_16x16x32_bf16 v[36:39], v[112:115], v[0:3], 0
	v_mfma_f32_16x16x32_bf16 v[36:39], v[116:119], v[4:7], v[36:39]
	ds_read_b128 v[112:115], v162 offset:6912
	ds_read_b128 v[116:119], v162 offset:6976
	s_waitcnt lgkmcnt(2)
	v_mfma_f32_16x16x32_bf16 v[40:43], v[104:107], v[0:3], 0
	v_mfma_f32_16x16x32_bf16 v[40:43], v[108:111], v[4:7], v[40:43]
	ds_read_b128 v[104:107], v162 offset:9216
	ds_read_b128 v[108:111], v162 offset:9280
	s_waitcnt lgkmcnt(2)
	v_mfma_f32_16x16x32_bf16 v[44:47], v[112:115], v[0:3], 0
	v_mfma_f32_16x16x32_bf16 v[44:47], v[116:119], v[4:7], v[44:47]
	ds_read_b128 v[112:115], v162 offset:11520
	ds_read_b128 v[116:119], v162 offset:11584
	s_waitcnt lgkmcnt(2)
	v_mfma_f32_16x16x32_bf16 v[48:51], v[104:107], v[0:3], 0
	v_mfma_f32_16x16x32_bf16 v[48:51], v[108:111], v[4:7], v[48:51]
	ds_read_b128 v[104:107], v162 offset:13824
	ds_read_b128 v[108:111], v162 offset:13888
	s_waitcnt lgkmcnt(2)
	v_mfma_f32_16x16x32_bf16 v[52:55], v[112:115], v[0:3], 0
	v_mfma_f32_16x16x32_bf16 v[52:55], v[116:119], v[4:7], v[52:55]
	ds_read_b128 v[112:115], v162 offset:16128
	ds_read_b128 v[116:119], v162 offset:16192
	s_waitcnt lgkmcnt(2)
	v_mfma_f32_16x16x32_bf16 v[56:59], v[104:107], v[0:3], 0
	v_mfma_f32_16x16x32_bf16 v[56:59], v[108:111], v[4:7], v[56:59]
	ds_read_b128 v[104:107], v162 offset:18432
	ds_read_b128 v[108:111], v162 offset:18496
	s_waitcnt lgkmcnt(2)
	v_mfma_f32_16x16x32_bf16 v[60:63], v[112:115], v[0:3], 0
	v_mfma_f32_16x16x32_bf16 v[60:63], v[116:119], v[4:7], v[60:63]
	s_waitcnt lgkmcnt(0)
	v_mfma_f32_16x16x32_bf16 v[64:67], v[104:107], v[0:3], 0
	v_mfma_f32_16x16x32_bf16 v[64:67], v[108:111], v[4:7], v[64:67]
	ds_read2_b32 v[122:123], v175 offset0:128 offset1:129
	ds_read2_b32 v[120:121], v175 offset0:130 offset1:131
	ds_read2_b32 v[126:127], v175 offset0:112 offset1:113
	ds_read2_b32 v[124:125], v175 offset0:114 offset1:115
	ds_read2_b32 v[130:131], v175 offset0:96 offset1:97
	ds_read2_b32 v[128:129], v175 offset0:98 offset1:99
	ds_read2_b32 v[134:135], v175 offset0:80 offset1:81
	ds_read2_b32 v[132:133], v175 offset0:82 offset1:83
	ds_read2_b32 v[138:139], v175 offset0:64 offset1:65
	ds_read2_b32 v[136:137], v175 offset0:66 offset1:67
	ds_read2_b32 v[142:143], v175 offset0:48 offset1:49
	ds_read2_b32 v[140:141], v175 offset0:50 offset1:51
	ds_read2_b32 v[146:147], v175 offset0:32 offset1:33
	ds_read2_b32 v[144:145], v175 offset0:34 offset1:35
	ds_read2_b32 v[150:151], v175 offset0:16 offset1:17
	ds_read2_b32 v[148:149], v175 offset0:18 offset1:19
	ds_read2_b32 v[154:155], v175 offset0:0 offset1:1
	ds_read2_b32 v[152:153], v175 offset0:2 offset1:3
	s_waitcnt lgkmcnt(0)
	s_nop 4
	v_fma_f32 v32, v32, s50, v121
	v_fma_f32 v33, v33, s50, v120
	v_fma_f32 v34, v34, s50, v123
	v_fma_f32 v35, v35, s50, v122
	v_fma_f32 v36, v36, s50, v125
	v_fma_f32 v37, v37, s50, v124
	v_fma_f32 v38, v38, s50, v127
	v_fma_f32 v39, v39, s50, v126
	v_fma_f32 v40, v40, s50, v129
	v_fma_f32 v41, v41, s50, v128
	v_fma_f32 v42, v42, s50, v131
	v_fma_f32 v43, v43, s50, v130
	v_fma_f32 v44, v44, s50, v133
	v_fma_f32 v45, v45, s50, v132
	v_fma_f32 v46, v46, s50, v135
	v_fma_f32 v47, v47, s50, v134
	v_fma_f32 v48, v48, s50, v137
	v_fma_f32 v49, v49, s50, v136
	v_fma_f32 v50, v50, s50, v139
	v_fma_f32 v51, v51, s50, v138
	v_fma_f32 v52, v52, s50, v141
	v_fma_f32 v53, v53, s50, v140
	v_fma_f32 v54, v54, s50, v143
	v_fma_f32 v55, v55, s50, v142
	v_fma_f32 v56, v56, s50, v145
	v_fma_f32 v57, v57, s50, v144
	v_fma_f32 v58, v58, s50, v147
	v_fma_f32 v59, v59, s50, v146
	v_fma_f32 v60, v60, s50, v149
	v_fma_f32 v61, v61, s50, v148
	v_fma_f32 v62, v62, s50, v151
	v_fma_f32 v63, v63, s50, v150
	v_fma_f32 v64, v64, s50, v153
	v_fma_f32 v65, v65, s50, v152
	v_fma_f32 v66, v66, s50, v155
	v_fma_f32 v67, v67, s50, v154
	v_mov_b32_e32 v176, 0xff800000
	v_cndmask_b32_e64 v32, v32, v176, s[40:41]
	v_cndmask_b32_e64 v64, v176, v64, s[40:41]
	v_cndmask_b32_e64 v33, v33, v176, s[42:43]
	v_cndmask_b32_e64 v65, v176, v65, s[42:43]
	v_cndmask_b32_e64 v34, v34, v176, s[44:45]
	v_cndmask_b32_e64 v66, v176, v66, s[44:45]
	v_cndmask_b32_e64 v35, v35, v176, s[46:47]
	v_cndmask_b32_e64 v67, v176, v67, s[46:47]
	s_cmp_lt_u32 0, s29
	s_cbranch_scc0 .Lm1b_h0_nomask
	v_mov_b32_e32 v32, 0xff800000
	v_mov_b32_e32 v33, 0xff800000
	v_mov_b32_e32 v34, 0xff800000
	v_mov_b32_e32 v35, 0xff800000
	s_cmp_lt_u32 1, s29
	s_cbranch_scc0 .Lm1b_h0_nomask
	v_mov_b32_e32 v36, 0xff800000
	v_mov_b32_e32 v37, 0xff800000
	v_mov_b32_e32 v38, 0xff800000
	v_mov_b32_e32 v39, 0xff800000
	s_cmp_lt_u32 2, s29
	s_cbranch_scc0 .Lm1b_h0_nomask
	v_mov_b32_e32 v40, 0xff800000
	v_mov_b32_e32 v41, 0xff800000
	v_mov_b32_e32 v42, 0xff800000
	v_mov_b32_e32 v43, 0xff800000
	s_cmp_lt_u32 3, s29
	s_cbranch_scc0 .Lm1b_h0_nomask
	v_mov_b32_e32 v44, 0xff800000
	v_mov_b32_e32 v45, 0xff800000
	v_mov_b32_e32 v46, 0xff800000
	v_mov_b32_e32 v47, 0xff800000
	s_cmp_lt_u32 4, s29
	s_cbranch_scc0 .Lm1b_h0_nomask
	v_mov_b32_e32 v48, 0xff800000
	v_mov_b32_e32 v49, 0xff800000
	v_mov_b32_e32 v50, 0xff800000
	v_mov_b32_e32 v51, 0xff800000
	s_cmp_lt_u32 5, s29
	s_cbranch_scc0 .Lm1b_h0_nomask
	v_mov_b32_e32 v52, 0xff800000
	v_mov_b32_e32 v53, 0xff800000
	v_mov_b32_e32 v54, 0xff800000
	v_mov_b32_e32 v55, 0xff800000
	s_cmp_lt_u32 6, s29
	s_cbranch_scc0 .Lm1b_h0_nomask
	v_mov_b32_e32 v56, 0xff800000
	v_mov_b32_e32 v57, 0xff800000
	v_mov_b32_e32 v58, 0xff800000
	v_mov_b32_e32 v59, 0xff800000
	s_cmp_lt_u32 7, s29
	s_cbranch_scc0 .Lm1b_h0_nomask
	v_mov_b32_e32 v60, 0xff800000
	v_mov_b32_e32 v61, 0xff800000
	v_mov_b32_e32 v62, 0xff800000
	v_mov_b32_e32 v63, 0xff800000
; #define LAS __attribute__((address_space(3)))
; DI unsigned short f2bf(float f) { return (unsigned short)(pk2(f, 0.f) & 0xffffu); }
; DI float sum16(float v) { v += __shfl_xor(v, 1); v += __shfl_xor(v, 2); v += __shfl_xor(v, 4); v += __shfl_xor(v, 8); return v; }
; DI float max16(float v) { v = fmaxf(v, __shfl_xor(v, 1)); v = fmaxf(v, __shfl_xor(v, 2)); v = fmaxf(v, __shfl_xor(v, 4)); v = fmaxf(v, __shfl_xor(v, 8)); return v; }
; __global__ void __launch_bounds__(512, 2) fwd_megakernel(Args args) {
;     ...
;                         float sm[4];
; #pragma unroll
;                         for (int j = 0; j < 4; ++j) {
;                             const int i = 16 * wave + q4 * 4 + j; float m = -INFINITY;
; #pragma unroll
;                             for (int kk = 0; kk < 9; ++kk) {
;                                 const int jk = 16 * (wave + kk) + r16, dist = i - jk + 128;
;                                 const bool ok = (dist >= 0) && (dist < 128) && (nb > 0 || jk >= 128);
;                                 const float sv = ok ? sc[kk][j] * 0.125f + s_bias[hq * 128 + (dist & 127)] : -INFINITY;
;                                 sc[kk][j] = sv; m = fmaxf(m, sv);
;                             }
;                             m = fmaxf(max16(m), sink);
;                             float su = 0.f;
; #pragma unroll
;                             for (int kk = 0; kk < 9; ++kk) { const float p = __expf(sc[kk][j] - m); sc[kk][j] = p; su += p; }
;                             sm[j] = sum16(su) + __expf(sink - m);
;                         }
; #pragma unroll
;                         for (int kk = 0; kk < 9; ++kk)
; #pragma unroll
;                             for (int j = 0; j < 4; ++j) Ps[(q4 * 4 + j) * 168 + kk * 16 + r16] = f2bf(sc[kk][j]);
;                         *(LAS u32x2*)(Ps + (lane >> 2) * 168 + 144 + (lane & 3) * 4) = (u32x2){0u, 0u};
.Lm1b_h0_nomask:
	v_max3_f32 v170, v32, v33, v34
	v_max3_f32 v170, v170, v35, v36
	v_max3_f32 v170, v170, v37, v38
	v_max3_f32 v170, v170, v39, v40
	v_max3_f32 v170, v170, v41, v42
	v_max3_f32 v170, v170, v43, v44
	v_max3_f32 v170, v170, v45, v46
	v_max3_f32 v170, v170, v47, v48
	v_max3_f32 v170, v170, v49, v50
	v_max3_f32 v170, v170, v51, v52
	v_max3_f32 v170, v170, v53, v54
	v_max3_f32 v170, v170, v55, v56
	v_max3_f32 v170, v170, v57, v58
	v_max3_f32 v170, v170, v59, v60
	v_max3_f32 v170, v170, v61, v62
	v_max3_f32 v170, v170, v63, v64
	v_max3_f32 v170, v170, v65, v66
	v_max_f32_e32 v170, v170, v67
	ds_bpermute_b32 v177, v173, v170
	s_waitcnt lgkmcnt(0)
	v_max_f32_e32 v170, v170, v177
	ds_bpermute_b32 v177, v174, v170
	s_waitcnt lgkmcnt(0)
	v_max_f32_e32 v170, v170, v177
	v_max_f32_e32 v170, s36, v170
	v_mul_f32_e32 v178, 0x3fb8aa3b, v170
	v_fma_f32 v32, v32, v179, -v178
	v_fma_f32 v33, v33, v179, -v178
	v_fma_f32 v34, v34, v179, -v178
	v_fma_f32 v35, v35, v179, -v178
	v_fma_f32 v36, v36, v179, -v178
	v_fma_f32 v37, v37, v179, -v178
	v_fma_f32 v38, v38, v179, -v178
	v_fma_f32 v39, v39, v179, -v178
	v_fma_f32 v40, v40, v179, -v178
	v_fma_f32 v41, v41, v179, -v178
	v_fma_f32 v42, v42, v179, -v178
	v_fma_f32 v43, v43, v179, -v178
	v_fma_f32 v44, v44, v179, -v178
	v_fma_f32 v45, v45, v179, -v178
	v_fma_f32 v46, v46, v179, -v178
	v_fma_f32 v47, v47, v179, -v178
	v_fma_f32 v48, v48, v179, -v178
	v_fma_f32 v49, v49, v179, -v178
	v_fma_f32 v50, v50, v179, -v178
	v_fma_f32 v51, v51, v179, -v178
	v_fma_f32 v52, v52, v179, -v178
	v_fma_f32 v53, v53, v179, -v178
	v_fma_f32 v54, v54, v179, -v178
	v_fma_f32 v55, v55, v179, -v178
	v_fma_f32 v56, v56, v179, -v178
	v_fma_f32 v57, v57, v179, -v178
	v_fma_f32 v58, v58, v179, -v178
	v_fma_f32 v59, v59, v179, -v178
	v_fma_f32 v60, v60, v179, -v178
	v_fma_f32 v61, v61, v179, -v178
	v_fma_f32 v62, v62, v179, -v178
	v_fma_f32 v63, v63, v179, -v178
	v_fma_f32 v64, v64, v179, -v178
	v_fma_f32 v65, v65, v179, -v178
	v_fma_f32 v66, v66, v179, -v178
	v_fma_f32 v67, v67, v179, -v178
	v_exp_f32_e32 v32, v32
	v_exp_f32_e32 v33, v33
	v_exp_f32_e32 v34, v34
	v_exp_f32_e32 v35, v35
	v_exp_f32_e32 v36, v36
	v_exp_f32_e32 v37, v37
	v_exp_f32_e32 v38, v38
	v_exp_f32_e32 v39, v39
	v_exp_f32_e32 v40, v40
	v_exp_f32_e32 v41, v41
	v_exp_f32_e32 v42, v42
	v_exp_f32_e32 v43, v43
	v_exp_f32_e32 v44, v44
	v_exp_f32_e32 v45, v45
	v_exp_f32_e32 v46, v46
	v_exp_f32_e32 v47, v47
	v_exp_f32_e32 v48, v48
	v_exp_f32_e32 v49, v49
	v_exp_f32_e32 v50, v50
	v_exp_f32_e32 v51, v51
	v_exp_f32_e32 v52, v52
	v_exp_f32_e32 v53, v53
	v_exp_f32_e32 v54, v54
	v_exp_f32_e32 v55, v55
	v_exp_f32_e32 v56, v56
	v_exp_f32_e32 v57, v57
	v_exp_f32_e32 v58, v58
	v_exp_f32_e32 v59, v59
	v_exp_f32_e32 v60, v60
	v_exp_f32_e32 v61, v61
	v_exp_f32_e32 v62, v62
	v_exp_f32_e32 v63, v63
	v_exp_f32_e32 v64, v64
	v_exp_f32_e32 v65, v65
	v_exp_f32_e32 v66, v66
	v_exp_f32_e32 v67, v67
	s_nop 0
	v_add_f32_e32 v180, v32, v36
	v_add_f32_e32 v181, v33, v37
	v_add_f32_e32 v182, v34, v38
	v_add_f32_e32 v183, v35, v39
	v_add_f32_e32 v180, v180, v40
	v_add_f32_e32 v181, v181, v41
	v_add_f32_e32 v182, v182, v42
	v_add_f32_e32 v183, v183, v43
	v_add_f32_e32 v180, v180, v44
	v_add_f32_e32 v181, v181, v45
	v_add_f32_e32 v182, v182, v46
	v_add_f32_e32 v183, v183, v47
	v_add_f32_e32 v180, v180, v48
	v_add_f32_e32 v181, v181, v49
	v_add_f32_e32 v182, v182, v50
	v_add_f32_e32 v183, v183, v51
	v_add_f32_e32 v180, v180, v52
	v_add_f32_e32 v181, v181, v53
	v_add_f32_e32 v182, v182, v54
	v_add_f32_e32 v183, v183, v55
	v_add_f32_e32 v180, v180, v56
	v_add_f32_e32 v181, v181, v57
	v_add_f32_e32 v182, v182, v58
	v_add_f32_e32 v183, v183, v59
	v_add_f32_e32 v180, v180, v60
	v_add_f32_e32 v181, v181, v61
	v_add_f32_e32 v182, v182, v62
	v_add_f32_e32 v183, v183, v63
	v_add_f32_e32 v180, v180, v64
	v_add_f32_e32 v181, v181, v65
	v_add_f32_e32 v182, v182, v66
	v_add_f32_e32 v183, v183, v67
	v_add_f32_e32 v180, v180, v181
	v_add_f32_e32 v182, v182, v183
	v_add_f32_e32 v171, v180, v182
	ds_bpermute_b32 v177, v173, v171
	v_cvt_pk_bf16_f32 v84, v32, v33
	v_cvt_pk_bf16_f32 v85, v34, v35
	v_cvt_pk_bf16_f32 v86, v36, v37
	v_cvt_pk_bf16_f32 v87, v38, v39
	v_cvt_pk_bf16_f32 v88, v40, v41
	v_cvt_pk_bf16_f32 v89, v42, v43
	v_cvt_pk_bf16_f32 v90, v44, v45
	v_cvt_pk_bf16_f32 v91, v46, v47
	v_cvt_pk_bf16_f32 v92, v48, v49
	v_cvt_pk_bf16_f32 v93, v50, v51
	v_cvt_pk_bf16_f32 v94, v52, v53
	v_cvt_pk_bf16_f32 v95, v54, v55
	v_cvt_pk_bf16_f32 v96, v56, v57
	v_cvt_pk_bf16_f32 v97, v58, v59
	v_cvt_pk_bf16_f32 v98, v60, v61
	v_cvt_pk_bf16_f32 v99, v62, v63
	v_cvt_pk_bf16_f32 v100, v64, v65
	v_cvt_pk_bf16_f32 v101, v66, v67
	v_mov_b32_e32 v102, 0
	v_mov_b32_e32 v103, 0
	s_waitcnt lgkmcnt(0)
	v_add_f32_e32 v171, v171, v177
	ds_bpermute_b32 v177, v174, v171
	v_sub_f32_e32 v176, s36, v170
	v_mul_f32_e32 v176, 0x3fb8aa3b, v176
	v_exp_f32_e32 v176, v176
	ds_read_b64_tr_b16 v[120:121], v163 offset:0
	ds_read_b64_tr_b16 v[122:123], v163 offset:2304
	ds_read_b64_tr_b16 v[124:125], v163 offset:32
	ds_read_b64_tr_b16 v[126:127], v163 offset:2336
	ds_read_b64_tr_b16 v[128:129], v163 offset:64
	ds_read_b64_tr_b16 v[130:131], v163 offset:2368
	ds_read_b64_tr_b16 v[132:133], v163 offset:96
	ds_read_b64_tr_b16 v[134:135], v163 offset:2400
	s_waitcnt lgkmcnt(8)
	v_add_f32_e32 v171, v171, v177
	v_add_f32_e32 v171, v171, v176
	s_waitcnt lgkmcnt(0)
; DI unsigned short f2bf(float f) { return (unsigned short)(pk2(f, 0.f) & 0xffffu); }
; DI float sum16(float v) { v += __shfl_xor(v, 1); v += __shfl_xor(v, 2); v += __shfl_xor(v, 4); v += __shfl_xor(v, 8); return v; }
; DI f32x4 mfma16(bf16x8 a, bf16x8 b, f32x4 c) { return __builtin_amdgcn_mfma_f32_16x16x32_bf16(a, b, c, 0, 0, 0); }
; __global__ void __launch_bounds__(512, 2) fwd_megakernel(Args args) {
;     ...
;                         f32x4 oa[4];
; #pragma unroll
;                         for (int dt = 0; dt < 4; ++dt) oa[dt] = (f32x4){0.f, 0.f, 0.f, 0.f};
; #pragma unroll
;                         for (int ks = 0; ks < 5; ++ks) {
;                             const bf16x8 pa = lds_frag(Ps, r16, 168, ks * 32 + q4 * 8);
; #pragma unroll
;                             for (int dt = 0; dt < 4; ++dt) oa[dt] = mfma16(pa, lds_frag(VT, 16 * dt + r16, 280, 16 * wave + ks * 32 + q4 * 8), oa[dt]);
;                         }
; #pragma unroll
;                         for (int j = 0; j < 4; ++j) { const float inv = 1.f / sm[j];
; #pragma unroll
;                             for (int dt = 0; dt < 4; ++dt) { const float o = oa[dt][j] * inv; ssr[j] += o * o; og[hq][dt][j] = o; } }
;                     }
;                 }
; #pragma unroll
;                 for (int hq = 0; hq < 4; ++hq) {
; #pragma unroll
;                     for (int j = 0; j < 4; ++j) {
;                         const size_t row = grow0 + 16 * wave + q4 * 4 + j; float ss = 0.f;
; #pragma unroll
;                         for (int dt = 0; dt < 4; ++dt) { const float o = og[hq][dt][j]; ss += o * o; Yg[row * DM + 512 + hq * 64 + 16 * dt + r16] = f2bf(o); }
;                         ss = sum16(ss);
;                         if (r16 == 0) mss_a[(size_t)hq * MTOK + row] = ss;
;                     }
	ds_read_b64_tr_b16 v[136:137], v163 offset:4608
	ds_read_b64_tr_b16 v[138:139], v163 offset:6912
	ds_read_b64_tr_b16 v[140:141], v163 offset:4640
	ds_read_b64_tr_b16 v[142:143], v163 offset:6944
	ds_read_b64_tr_b16 v[144:145], v163 offset:4672
	ds_read_b64_tr_b16 v[146:147], v163 offset:6976
	ds_read_b64_tr_b16 v[148:149], v163 offset:4704
	ds_read_b64_tr_b16 v[150:151], v163 offset:7008
	v_mfma_f32_16x16x32_bf16 v[68:71], v[120:123], v[84:87], 0
	v_mfma_f32_16x16x32_bf16 v[72:75], v[124:127], v[84:87], 0
	v_mfma_f32_16x16x32_bf16 v[76:79], v[128:131], v[84:87], 0
	v_mfma_f32_16x16x32_bf16 v[80:83], v[132:135], v[84:87], 0
	s_waitcnt lgkmcnt(0)
	ds_read_b64_tr_b16 v[120:121], v163 offset:9216
	ds_read_b64_tr_b16 v[122:123], v163 offset:11520
	ds_read_b64_tr_b16 v[124:125], v163 offset:9248
	ds_read_b64_tr_b16 v[126:127], v163 offset:11552
	ds_read_b64_tr_b16 v[128:129], v163 offset:9280
	ds_read_b64_tr_b16 v[130:131], v163 offset:11584
	ds_read_b64_tr_b16 v[132:133], v163 offset:9312
	ds_read_b64_tr_b16 v[134:135], v163 offset:11616
	v_mfma_f32_16x16x32_bf16 v[68:71], v[136:139], v[88:91], v[68:71]
	v_mfma_f32_16x16x32_bf16 v[72:75], v[140:143], v[88:91], v[72:75]
	v_mfma_f32_16x16x32_bf16 v[76:79], v[144:147], v[88:91], v[76:79]
	v_mfma_f32_16x16x32_bf16 v[80:83], v[148:151], v[88:91], v[80:83]
	s_waitcnt lgkmcnt(0)
	ds_read_b64_tr_b16 v[136:137], v163 offset:13824
	ds_read_b64_tr_b16 v[138:139], v163 offset:16128
	ds_read_b64_tr_b16 v[140:141], v163 offset:13856
	ds_read_b64_tr_b16 v[142:143], v163 offset:16160
	ds_read_b64_tr_b16 v[144:145], v163 offset:13888
	ds_read_b64_tr_b16 v[146:147], v163 offset:16192
	ds_read_b64_tr_b16 v[148:149], v163 offset:13920
	ds_read_b64_tr_b16 v[150:151], v163 offset:16224
	v_mfma_f32_16x16x32_bf16 v[68:71], v[120:123], v[92:95], v[68:71]
	v_mfma_f32_16x16x32_bf16 v[72:75], v[124:127], v[92:95], v[72:75]
	v_mfma_f32_16x16x32_bf16 v[76:79], v[128:131], v[92:95], v[76:79]
	v_mfma_f32_16x16x32_bf16 v[80:83], v[132:135], v[92:95], v[80:83]
	s_waitcnt lgkmcnt(0)
	ds_read_b64_tr_b16 v[120:121], v163 offset:18432
	ds_read_b64_tr_b16 v[122:123], v163 offset:20736
	ds_read_b64_tr_b16 v[124:125], v163 offset:18464
	ds_read_b64_tr_b16 v[126:127], v163 offset:20768
	ds_read_b64_tr_b16 v[128:129], v163 offset:18496
	ds_read_b64_tr_b16 v[130:131], v163 offset:20800
	ds_read_b64_tr_b16 v[132:133], v163 offset:18528
	ds_read_b64_tr_b16 v[134:135], v163 offset:20832
	v_mfma_f32_16x16x32_bf16 v[68:71], v[136:139], v[96:99], v[68:71]
	v_mfma_f32_16x16x32_bf16 v[72:75], v[140:143], v[96:99], v[72:75]
	v_mfma_f32_16x16x32_bf16 v[76:79], v[144:147], v[96:99], v[76:79]
	v_mfma_f32_16x16x32_bf16 v[80:83], v[148:151], v[96:99], v[80:83]
	s_waitcnt lgkmcnt(0)
	v_mfma_f32_16x16x32_bf16 v[68:71], v[120:123], v[100:103], v[68:71]
	v_mfma_f32_16x16x32_bf16 v[72:75], v[124:127], v[100:103], v[72:75]
	v_mfma_f32_16x16x32_bf16 v[76:79], v[128:131], v[100:103], v[76:79]
	v_mfma_f32_16x16x32_bf16 v[80:83], v[132:135], v[100:103], v[80:83]
	v_rcp_f32_e32 v172, v171
	s_nop 7
	s_nop 3
	v_mul_f32_e32 v68, v68, v172
	v_mul_f32_e32 v69, v69, v172
	v_mul_f32_e32 v70, v70, v172
	v_mul_f32_e32 v71, v71, v172
	v_mul_f32_e32 v171, v68, v68
	v_fmac_f32_e32 v171, v69, v69
	v_fmac_f32_e32 v171, v70, v70
	v_fmac_f32_e32 v171, v71, v71
	v_cvt_pk_bf16_f32 v180, v68, v69
	v_cvt_pk_bf16_f32 v181, v70, v71
	global_store_dwordx2 v165, v[180:181], s[10:11] offset:0
	v_mul_f32_e32 v72, v72, v172
	v_mul_f32_e32 v73, v73, v172
	v_mul_f32_e32 v74, v74, v172
	v_mul_f32_e32 v75, v75, v172
	v_fmac_f32_e32 v171, v72, v72
	v_fmac_f32_e32 v171, v73, v73
	v_fmac_f32_e32 v171, v74, v74
	v_fmac_f32_e32 v171, v75, v75
	v_cvt_pk_bf16_f32 v180, v72, v73
	v_cvt_pk_bf16_f32 v181, v74, v75
	global_store_dwordx2 v165, v[180:181], s[10:11] offset:32
	v_mul_f32_e32 v76, v76, v172
	v_mul_f32_e32 v77, v77, v172
	v_mul_f32_e32 v78, v78, v172
	v_mul_f32_e32 v79, v79, v172
	v_fmac_f32_e32 v171, v76, v76
	v_fmac_f32_e32 v171, v77, v77
	v_fmac_f32_e32 v171, v78, v78
	v_fmac_f32_e32 v171, v79, v79
	v_cvt_pk_bf16_f32 v180, v76, v77
	v_cvt_pk_bf16_f32 v181, v78, v79
	global_store_dwordx2 v165, v[180:181], s[10:11] offset:64
	v_mul_f32_e32 v80, v80, v172
	v_mul_f32_e32 v81, v81, v172
	v_mul_f32_e32 v82, v82, v172
	v_mul_f32_e32 v83, v83, v172
	v_fmac_f32_e32 v171, v80, v80
	v_fmac_f32_e32 v171, v81, v81
	v_fmac_f32_e32 v171, v82, v82
	v_fmac_f32_e32 v171, v83, v83
	v_cvt_pk_bf16_f32 v180, v80, v81
	v_cvt_pk_bf16_f32 v181, v82, v83
	global_store_dwordx2 v165, v[180:181], s[10:11] offset:96
	ds_bpermute_b32 v177, v173, v171
	s_waitcnt lgkmcnt(0)
	v_add_f32_e32 v171, v171, v177
	ds_bpermute_b32 v177, v174, v171
	s_waitcnt lgkmcnt(0)
	v_add_f32_e32 v171, v171, v177
	s_mov_b64 exec, s[48:49]
	global_store_dword v166, v171, s[12:13]
	s_mov_b64 exec, -1
	s_add_u32 s30, s12, 131072
	s_addc_u32 s31, s13, 0
	v_add_u32_e32 v175, 512, v164
	ds_read_b128 v[104:107], v162 offset:0
	ds_read_b128 v[108:111], v162 offset:64
	ds_read_b128 v[112:115], v162 offset:2304
	ds_read_b128 v[116:119], v162 offset:2368
	s_waitcnt lgkmcnt(2)
	v_mfma_f32_16x16x32_bf16 v[32:35], v[104:107], v[8:11], 0
	v_mfma_f32_16x16x32_bf16 v[32:35], v[108:111], v[12:15], v[32:35]
	ds_read_b128 v[104:107], v162 offset:4608
	ds_read_b128 v[108:111], v162 offset:4672
	s_waitcnt lgkmcnt(2)
	v_mfma_f32_16x16x32_bf16 v[36:39], v[112:115], v[8:11], 0
	v_mfma_f32_16x16x32_bf16 v[36:39], v[116:119], v[12:15], v[36:39]
	ds_read_b128 v[112:115], v162 offset:6912
	ds_read_b128 v[116:119], v162 offset:6976
	s_waitcnt lgkmcnt(2)
; DI f32x4 mfma16(bf16x8 a, bf16x8 b, f32x4 c) { return __builtin_amdgcn_mfma_f32_16x16x32_bf16(a, b, c, 0, 0, 0); }
; __global__ void __launch_bounds__(512, 2) fwd_megakernel(Args args) {
;     ...
;                         f32x4 sc[9];
; #pragma unroll
;                         for (int kk = 0; kk < 9; ++kk) {
;                             const int krow = 16 * (wave + kk) + r16;
;                             f32x4 a = (f32x4){0.f, 0.f, 0.f, 0.f};
;                             a = mfma16(aq0, lds_frag(Ks, krow, 72, q4 * 8), a);
;                             a = mfma16(aq1, lds_frag(Ks, krow, 72, 32 + q4 * 8), a);
;                             sc[kk] = a;
;                         }
;                         float sm[4];
; #pragma unroll
;                         for (int j = 0; j < 4; ++j) {
;                             const int i = 16 * wave + q4 * 4 + j; float m = -INFINITY;
; #pragma unroll
;                             for (int kk = 0; kk < 9; ++kk) {
;                                 const int jk = 16 * (wave + kk) + r16, dist = i - jk + 128;
;                                 const bool ok = (dist >= 0) && (dist < 128) && (nb > 0 || jk >= 128);
;                                 const float sv = ok ? sc[kk][j] * 0.125f + s_bias[hq * 128 + (dist & 127)] : -INFINITY;
;                                 sc[kk][j] = sv; m = fmaxf(m, sv);
;                             }
	v_mfma_f32_16x16x32_bf16 v[40:43], v[104:107], v[8:11], 0
	v_mfma_f32_16x16x32_bf16 v[40:43], v[108:111], v[12:15], v[40:43]
	ds_read_b128 v[104:107], v162 offset:9216
	ds_read_b128 v[108:111], v162 offset:9280
	s_waitcnt lgkmcnt(2)
	v_mfma_f32_16x16x32_bf16 v[44:47], v[112:115], v[8:11], 0
	v_mfma_f32_16x16x32_bf16 v[44:47], v[116:119], v[12:15], v[44:47]
	ds_read_b128 v[112:115], v162 offset:11520
	ds_read_b128 v[116:119], v162 offset:11584
	s_waitcnt lgkmcnt(2)
	v_mfma_f32_16x16x32_bf16 v[48:51], v[104:107], v[8:11], 0
	v_mfma_f32_16x16x32_bf16 v[48:51], v[108:111], v[12:15], v[48:51]
	ds_read_b128 v[104:107], v162 offset:13824
	ds_read_b128 v[108:111], v162 offset:13888
	s_waitcnt lgkmcnt(2)
	v_mfma_f32_16x16x32_bf16 v[52:55], v[112:115], v[8:11], 0
	v_mfma_f32_16x16x32_bf16 v[52:55], v[116:119], v[12:15], v[52:55]
	ds_read_b128 v[112:115], v162 offset:16128
	ds_read_b128 v[116:119], v162 offset:16192
	s_waitcnt lgkmcnt(2)
	v_mfma_f32_16x16x32_bf16 v[56:59], v[104:107], v[8:11], 0
	v_mfma_f32_16x16x32_bf16 v[56:59], v[108:111], v[12:15], v[56:59]
	ds_read_b128 v[104:107], v162 offset:18432
	ds_read_b128 v[108:111], v162 offset:18496
	s_waitcnt lgkmcnt(2)
	v_mfma_f32_16x16x32_bf16 v[60:63], v[112:115], v[8:11], 0
	v_mfma_f32_16x16x32_bf16 v[60:63], v[116:119], v[12:15], v[60:63]
	s_waitcnt lgkmcnt(0)
	v_mfma_f32_16x16x32_bf16 v[64:67], v[104:107], v[8:11], 0
	v_mfma_f32_16x16x32_bf16 v[64:67], v[108:111], v[12:15], v[64:67]
	ds_read2_b32 v[122:123], v175 offset0:128 offset1:129
	ds_read2_b32 v[120:121], v175 offset0:130 offset1:131
	ds_read2_b32 v[126:127], v175 offset0:112 offset1:113
	ds_read2_b32 v[124:125], v175 offset0:114 offset1:115
	ds_read2_b32 v[130:131], v175 offset0:96 offset1:97
	ds_read2_b32 v[128:129], v175 offset0:98 offset1:99
	ds_read2_b32 v[134:135], v175 offset0:80 offset1:81
	ds_read2_b32 v[132:133], v175 offset0:82 offset1:83
	ds_read2_b32 v[138:139], v175 offset0:64 offset1:65
	ds_read2_b32 v[136:137], v175 offset0:66 offset1:67
	ds_read2_b32 v[142:143], v175 offset0:48 offset1:49
	ds_read2_b32 v[140:141], v175 offset0:50 offset1:51
	ds_read2_b32 v[146:147], v175 offset0:32 offset1:33
	ds_read2_b32 v[144:145], v175 offset0:34 offset1:35
	ds_read2_b32 v[150:151], v175 offset0:16 offset1:17
	ds_read2_b32 v[148:149], v175 offset0:18 offset1:19
	ds_read2_b32 v[154:155], v175 offset0:0 offset1:1
	ds_read2_b32 v[152:153], v175 offset0:2 offset1:3
	s_waitcnt lgkmcnt(0)
	s_nop 4
	v_fma_f32 v32, v32, s50, v121
	v_fma_f32 v33, v33, s50, v120
	v_fma_f32 v34, v34, s50, v123
	v_fma_f32 v35, v35, s50, v122
	v_fma_f32 v36, v36, s50, v125
	v_fma_f32 v37, v37, s50, v124
	v_fma_f32 v38, v38, s50, v127
	v_fma_f32 v39, v39, s50, v126
	v_fma_f32 v40, v40, s50, v129
	v_fma_f32 v41, v41, s50, v128
	v_fma_f32 v42, v42, s50, v131
	v_fma_f32 v43, v43, s50, v130
	v_fma_f32 v44, v44, s50, v133
	v_fma_f32 v45, v45, s50, v132
	v_fma_f32 v46, v46, s50, v135
	v_fma_f32 v47, v47, s50, v134
	v_fma_f32 v48, v48, s50, v137
	v_fma_f32 v49, v49, s50, v136
	v_fma_f32 v50, v50, s50, v139
	v_fma_f32 v51, v51, s50, v138
	v_fma_f32 v52, v52, s50, v141
	v_fma_f32 v53, v53, s50, v140
	v_fma_f32 v54, v54, s50, v143
	v_fma_f32 v55, v55, s50, v142
	v_fma_f32 v56, v56, s50, v145
	v_fma_f32 v57, v57, s50, v144
	v_fma_f32 v58, v58, s50, v147
	v_fma_f32 v59, v59, s50, v146
	v_fma_f32 v60, v60, s50, v149
	v_fma_f32 v61, v61, s50, v148
	v_fma_f32 v62, v62, s50, v151
	v_fma_f32 v63, v63, s50, v150
	v_fma_f32 v64, v64, s50, v153
	v_fma_f32 v65, v65, s50, v152
	v_fma_f32 v66, v66, s50, v155
	v_fma_f32 v67, v67, s50, v154
	v_mov_b32_e32 v176, 0xff800000
	v_cndmask_b32_e64 v32, v32, v176, s[40:41]
	v_cndmask_b32_e64 v64, v176, v64, s[40:41]
	v_cndmask_b32_e64 v33, v33, v176, s[42:43]
	v_cndmask_b32_e64 v65, v176, v65, s[42:43]
	v_cndmask_b32_e64 v34, v34, v176, s[44:45]
	v_cndmask_b32_e64 v66, v176, v66, s[44:45]
	v_cndmask_b32_e64 v35, v35, v176, s[46:47]
	v_cndmask_b32_e64 v67, v176, v67, s[46:47]
	s_cmp_lt_u32 0, s29
	s_cbranch_scc0 .Lm1b_h1_nomask
	v_mov_b32_e32 v32, 0xff800000
	v_mov_b32_e32 v33, 0xff800000
	v_mov_b32_e32 v34, 0xff800000
	v_mov_b32_e32 v35, 0xff800000
	s_cmp_lt_u32 1, s29
	s_cbranch_scc0 .Lm1b_h1_nomask
	v_mov_b32_e32 v36, 0xff800000
	v_mov_b32_e32 v37, 0xff800000
	v_mov_b32_e32 v38, 0xff800000
	v_mov_b32_e32 v39, 0xff800000
	s_cmp_lt_u32 2, s29
	s_cbranch_scc0 .Lm1b_h1_nomask
	v_mov_b32_e32 v40, 0xff800000
	v_mov_b32_e32 v41, 0xff800000
	v_mov_b32_e32 v42, 0xff800000
	v_mov_b32_e32 v43, 0xff800000
	s_cmp_lt_u32 3, s29
	s_cbranch_scc0 .Lm1b_h1_nomask
	v_mov_b32_e32 v44, 0xff800000
	v_mov_b32_e32 v45, 0xff800000
	v_mov_b32_e32 v46, 0xff800000
	v_mov_b32_e32 v47, 0xff800000
	s_cmp_lt_u32 4, s29
	s_cbranch_scc0 .Lm1b_h1_nomask
	v_mov_b32_e32 v48, 0xff800000
	v_mov_b32_e32 v49, 0xff800000
	v_mov_b32_e32 v50, 0xff800000
	v_mov_b32_e32 v51, 0xff800000
	s_cmp_lt_u32 5, s29
	s_cbranch_scc0 .Lm1b_h1_nomask
	v_mov_b32_e32 v52, 0xff800000
	v_mov_b32_e32 v53, 0xff800000
	v_mov_b32_e32 v54, 0xff800000
	v_mov_b32_e32 v55, 0xff800000
	s_cmp_lt_u32 6, s29
	s_cbranch_scc0 .Lm1b_h1_nomask
	v_mov_b32_e32 v56, 0xff800000
	v_mov_b32_e32 v57, 0xff800000
	v_mov_b32_e32 v58, 0xff800000
	v_mov_b32_e32 v59, 0xff800000
	s_cmp_lt_u32 7, s29
	s_cbranch_scc0 .Lm1b_h1_nomask
	v_mov_b32_e32 v60, 0xff800000
	v_mov_b32_e32 v61, 0xff800000
	v_mov_b32_e32 v62, 0xff800000
	v_mov_b32_e32 v63, 0xff800000
; #define LAS __attribute__((address_space(3)))
; DI unsigned short f2bf(float f) { return (unsigned short)(pk2(f, 0.f) & 0xffffu); }
; DI float sum16(float v) { v += __shfl_xor(v, 1); v += __shfl_xor(v, 2); v += __shfl_xor(v, 4); v += __shfl_xor(v, 8); return v; }
; DI float max16(float v) { v = fmaxf(v, __shfl_xor(v, 1)); v = fmaxf(v, __shfl_xor(v, 2)); v = fmaxf(v, __shfl_xor(v, 4)); v = fmaxf(v, __shfl_xor(v, 8)); return v; }
; __global__ void __launch_bounds__(512, 2) fwd_megakernel(Args args) {
;     ...
;                         float sm[4];
; #pragma unroll
;                         for (int j = 0; j < 4; ++j) {
;                             const int i = 16 * wave + q4 * 4 + j; float m = -INFINITY;
; #pragma unroll
;                             for (int kk = 0; kk < 9; ++kk) {
;                                 const int jk = 16 * (wave + kk) + r16, dist = i - jk + 128;
;                                 const bool ok = (dist >= 0) && (dist < 128) && (nb > 0 || jk >= 128);
;                                 const float sv = ok ? sc[kk][j] * 0.125f + s_bias[hq * 128 + (dist & 127)] : -INFINITY;
;                                 sc[kk][j] = sv; m = fmaxf(m, sv);
;                             }
;                             m = fmaxf(max16(m), sink);
;                             float su = 0.f;
; #pragma unroll
;                             for (int kk = 0; kk < 9; ++kk) { const float p = __expf(sc[kk][j] - m); sc[kk][j] = p; su += p; }
;                             sm[j] = sum16(su) + __expf(sink - m);
;                         }
; #pragma unroll
;                         for (int kk = 0; kk < 9; ++kk)
; #pragma unroll
;                             for (int j = 0; j < 4; ++j) Ps[(q4 * 4 + j) * 168 + kk * 16 + r16] = f2bf(sc[kk][j]);
;                         *(LAS u32x2*)(Ps + (lane >> 2) * 168 + 144 + (lane & 3) * 4) = (u32x2){0u, 0u};
.Lm1b_h1_nomask:
	v_max3_f32 v170, v32, v33, v34
	v_max3_f32 v170, v170, v35, v36
	v_max3_f32 v170, v170, v37, v38
	v_max3_f32 v170, v170, v39, v40
	v_max3_f32 v170, v170, v41, v42
	v_max3_f32 v170, v170, v43, v44
	v_max3_f32 v170, v170, v45, v46
	v_max3_f32 v170, v170, v47, v48
	v_max3_f32 v170, v170, v49, v50
	v_max3_f32 v170, v170, v51, v52
	v_max3_f32 v170, v170, v53, v54
	v_max3_f32 v170, v170, v55, v56
	v_max3_f32 v170, v170, v57, v58
	v_max3_f32 v170, v170, v59, v60
	v_max3_f32 v170, v170, v61, v62
	v_max3_f32 v170, v170, v63, v64
	v_max3_f32 v170, v170, v65, v66
	v_max_f32_e32 v170, v170, v67
	ds_bpermute_b32 v177, v173, v170
	s_waitcnt lgkmcnt(0)
	v_max_f32_e32 v170, v170, v177
	ds_bpermute_b32 v177, v174, v170
	s_waitcnt lgkmcnt(0)
	v_max_f32_e32 v170, v170, v177
	v_max_f32_e32 v170, s37, v170
	v_mul_f32_e32 v178, 0x3fb8aa3b, v170
	v_fma_f32 v32, v32, v179, -v178
	v_fma_f32 v33, v33, v179, -v178
	v_fma_f32 v34, v34, v179, -v178
	v_fma_f32 v35, v35, v179, -v178
	v_fma_f32 v36, v36, v179, -v178
	v_fma_f32 v37, v37, v179, -v178
	v_fma_f32 v38, v38, v179, -v178
	v_fma_f32 v39, v39, v179, -v178
	v_fma_f32 v40, v40, v179, -v178
	v_fma_f32 v41, v41, v179, -v178
	v_fma_f32 v42, v42, v179, -v178
	v_fma_f32 v43, v43, v179, -v178
	v_fma_f32 v44, v44, v179, -v178
	v_fma_f32 v45, v45, v179, -v178
	v_fma_f32 v46, v46, v179, -v178
	v_fma_f32 v47, v47, v179, -v178
	v_fma_f32 v48, v48, v179, -v178
	v_fma_f32 v49, v49, v179, -v178
	v_fma_f32 v50, v50, v179, -v178
	v_fma_f32 v51, v51, v179, -v178
	v_fma_f32 v52, v52, v179, -v178
	v_fma_f32 v53, v53, v179, -v178
	v_fma_f32 v54, v54, v179, -v178
	v_fma_f32 v55, v55, v179, -v178
	v_fma_f32 v56, v56, v179, -v178
	v_fma_f32 v57, v57, v179, -v178
	v_fma_f32 v58, v58, v179, -v178
	v_fma_f32 v59, v59, v179, -v178
	v_fma_f32 v60, v60, v179, -v178
	v_fma_f32 v61, v61, v179, -v178
	v_fma_f32 v62, v62, v179, -v178
	v_fma_f32 v63, v63, v179, -v178
	v_fma_f32 v64, v64, v179, -v178
	v_fma_f32 v65, v65, v179, -v178
	v_fma_f32 v66, v66, v179, -v178
	v_fma_f32 v67, v67, v179, -v178
	v_exp_f32_e32 v32, v32
	v_exp_f32_e32 v33, v33
	v_exp_f32_e32 v34, v34
	v_exp_f32_e32 v35, v35
	v_exp_f32_e32 v36, v36
	v_exp_f32_e32 v37, v37
	v_exp_f32_e32 v38, v38
	v_exp_f32_e32 v39, v39
	v_exp_f32_e32 v40, v40
	v_exp_f32_e32 v41, v41
	v_exp_f32_e32 v42, v42
	v_exp_f32_e32 v43, v43
	v_exp_f32_e32 v44, v44
	v_exp_f32_e32 v45, v45
	v_exp_f32_e32 v46, v46
	v_exp_f32_e32 v47, v47
	v_exp_f32_e32 v48, v48
	v_exp_f32_e32 v49, v49
	v_exp_f32_e32 v50, v50
	v_exp_f32_e32 v51, v51
	v_exp_f32_e32 v52, v52
	v_exp_f32_e32 v53, v53
	v_exp_f32_e32 v54, v54
	v_exp_f32_e32 v55, v55
	v_exp_f32_e32 v56, v56
	v_exp_f32_e32 v57, v57
	v_exp_f32_e32 v58, v58
	v_exp_f32_e32 v59, v59
	v_exp_f32_e32 v60, v60
	v_exp_f32_e32 v61, v61
	v_exp_f32_e32 v62, v62
	v_exp_f32_e32 v63, v63
	v_exp_f32_e32 v64, v64
	v_exp_f32_e32 v65, v65
	v_exp_f32_e32 v66, v66
	v_exp_f32_e32 v67, v67
	s_nop 0
	v_add_f32_e32 v180, v32, v36
	v_add_f32_e32 v181, v33, v37
	v_add_f32_e32 v182, v34, v38
	v_add_f32_e32 v183, v35, v39
	v_add_f32_e32 v180, v180, v40
	v_add_f32_e32 v181, v181, v41
	v_add_f32_e32 v182, v182, v42
	v_add_f32_e32 v183, v183, v43
	v_add_f32_e32 v180, v180, v44
	v_add_f32_e32 v181, v181, v45
	v_add_f32_e32 v182, v182, v46
	v_add_f32_e32 v183, v183, v47
	v_add_f32_e32 v180, v180, v48
	v_add_f32_e32 v181, v181, v49
	v_add_f32_e32 v182, v182, v50
	v_add_f32_e32 v183, v183, v51
	v_add_f32_e32 v180, v180, v52
	v_add_f32_e32 v181, v181, v53
	v_add_f32_e32 v182, v182, v54
	v_add_f32_e32 v183, v183, v55
	v_add_f32_e32 v180, v180, v56
	v_add_f32_e32 v181, v181, v57
	v_add_f32_e32 v182, v182, v58
	v_add_f32_e32 v183, v183, v59
	v_add_f32_e32 v180, v180, v60
	v_add_f32_e32 v181, v181, v61
	v_add_f32_e32 v182, v182, v62
	v_add_f32_e32 v183, v183, v63
	v_add_f32_e32 v180, v180, v64
	v_add_f32_e32 v181, v181, v65
	v_add_f32_e32 v182, v182, v66
	v_add_f32_e32 v183, v183, v67
	v_add_f32_e32 v180, v180, v181
	v_add_f32_e32 v182, v182, v183
	v_add_f32_e32 v171, v180, v182
	ds_bpermute_b32 v177, v173, v171
	v_cvt_pk_bf16_f32 v84, v32, v33
	v_cvt_pk_bf16_f32 v85, v34, v35
	v_cvt_pk_bf16_f32 v86, v36, v37
	v_cvt_pk_bf16_f32 v87, v38, v39
	v_cvt_pk_bf16_f32 v88, v40, v41
	v_cvt_pk_bf16_f32 v89, v42, v43
	v_cvt_pk_bf16_f32 v90, v44, v45
	v_cvt_pk_bf16_f32 v91, v46, v47
	v_cvt_pk_bf16_f32 v92, v48, v49
	v_cvt_pk_bf16_f32 v93, v50, v51
	v_cvt_pk_bf16_f32 v94, v52, v53
	v_cvt_pk_bf16_f32 v95, v54, v55
	v_cvt_pk_bf16_f32 v96, v56, v57
	v_cvt_pk_bf16_f32 v97, v58, v59
	v_cvt_pk_bf16_f32 v98, v60, v61
	v_cvt_pk_bf16_f32 v99, v62, v63
	v_cvt_pk_bf16_f32 v100, v64, v65
	v_cvt_pk_bf16_f32 v101, v66, v67
	v_mov_b32_e32 v102, 0
	v_mov_b32_e32 v103, 0
	s_waitcnt lgkmcnt(0)
	v_add_f32_e32 v171, v171, v177
	ds_bpermute_b32 v177, v174, v171
	v_sub_f32_e32 v176, s37, v170
	v_mul_f32_e32 v176, 0x3fb8aa3b, v176
	v_exp_f32_e32 v176, v176
	ds_read_b64_tr_b16 v[120:121], v163 offset:0
	ds_read_b64_tr_b16 v[122:123], v163 offset:2304
	ds_read_b64_tr_b16 v[124:125], v163 offset:32
	ds_read_b64_tr_b16 v[126:127], v163 offset:2336
	ds_read_b64_tr_b16 v[128:129], v163 offset:64
	ds_read_b64_tr_b16 v[130:131], v163 offset:2368
	ds_read_b64_tr_b16 v[132:133], v163 offset:96
	ds_read_b64_tr_b16 v[134:135], v163 offset:2400
	s_waitcnt lgkmcnt(8)
	v_add_f32_e32 v171, v171, v177
	v_add_f32_e32 v171, v171, v176
	s_waitcnt lgkmcnt(0)
; DI unsigned short f2bf(float f) { return (unsigned short)(pk2(f, 0.f) & 0xffffu); }
; DI float sum16(float v) { v += __shfl_xor(v, 1); v += __shfl_xor(v, 2); v += __shfl_xor(v, 4); v += __shfl_xor(v, 8); return v; }
; __global__ void __launch_bounds__(512, 2) fwd_megakernel(Args args) {
;     ...
;                 for (int kvh = 0; kvh < 2; ++kvh) {
;                     if (kvh) __syncthreads();
;                     {
;                         u32x4 kq[4], vq[4];
; #pragma unroll
;                         for (int k = 0; k < 4; ++k) {
;                             const int it = tid + 512 * k, j = it >> 3, d8 = (it & 7) * 8;
;                             kq[k] = (u32x4){0u, 0u, 0u, 0u}; vq[k] = (u32x4){0u, 0u, 0u, 0u};
;                             if (nb > 0 || j >= 128) { const bf16* src = proj + (grow0 + j - 128) * NPROJ + kvh * 64 + d8; kq[k] = *(const u32x4*)(src + PC_K); vq[k] = *(const u32x4*)(src + PC_V); }
;                         }
;     ...
;                         f32x4 oa[4];
; #pragma unroll
;                         for (int dt = 0; dt < 4; ++dt) oa[dt] = (f32x4){0.f, 0.f, 0.f, 0.f};
; #pragma unroll
;                         for (int ks = 0; ks < 5; ++ks) {
;                             const bf16x8 pa = lds_frag(Ps, r16, 168, ks * 32 + q4 * 8);
; #pragma unroll
;                             for (int dt = 0; dt < 4; ++dt) oa[dt] = mfma16(pa, lds_frag(VT, 16 * dt + r16, 280, 16 * wave + ks * 32 + q4 * 8), oa[dt]);
;                         }
; #pragma unroll
;                         for (int j = 0; j < 4; ++j) { const float inv = 1.f / sm[j];
; #pragma unroll
;                             for (int dt = 0; dt < 4; ++dt) { const float o = oa[dt][j] * inv; ssr[j] += o * o; og[hq][dt][j] = o; } }
;                     }
;                 }
; #pragma unroll
;                 for (int hq = 0; hq < 4; ++hq) {
; #pragma unroll
;                     for (int j = 0; j < 4; ++j) {
;                         const size_t row = grow0 + 16 * wave + q4 * 4 + j; float ss = 0.f;
; #pragma unroll
;                         for (int dt = 0; dt < 4; ++dt) { const float o = og[hq][dt][j]; ss += o * o; Yg[row * DM + 512 + hq * 64 + 16 * dt + r16] = f2bf(o); }
;                         ss = sum16(ss);
;                         if (r16 == 0) mss_a[(size_t)hq * MTOK + row] = ss;
;                     }
	ds_read_b64_tr_b16 v[136:137], v163 offset:4608
	ds_read_b64_tr_b16 v[138:139], v163 offset:6912
	ds_read_b64_tr_b16 v[140:141], v163 offset:4640
	ds_read_b64_tr_b16 v[142:143], v163 offset:6944
	ds_read_b64_tr_b16 v[144:145], v163 offset:4672
	ds_read_b64_tr_b16 v[146:147], v163 offset:6976
	ds_read_b64_tr_b16 v[148:149], v163 offset:4704
	ds_read_b64_tr_b16 v[150:151], v163 offset:7008
	v_mfma_f32_16x16x32_bf16 v[68:71], v[120:123], v[84:87], 0
	v_mfma_f32_16x16x32_bf16 v[72:75], v[124:127], v[84:87], 0
	v_mfma_f32_16x16x32_bf16 v[76:79], v[128:131], v[84:87], 0
	v_mfma_f32_16x16x32_bf16 v[80:83], v[132:135], v[84:87], 0
	s_waitcnt lgkmcnt(0)
	ds_read_b64_tr_b16 v[120:121], v163 offset:9216
	ds_read_b64_tr_b16 v[122:123], v163 offset:11520
	ds_read_b64_tr_b16 v[124:125], v163 offset:9248
	ds_read_b64_tr_b16 v[126:127], v163 offset:11552
	ds_read_b64_tr_b16 v[128:129], v163 offset:9280
	ds_read_b64_tr_b16 v[130:131], v163 offset:11584
	ds_read_b64_tr_b16 v[132:133], v163 offset:9312
	ds_read_b64_tr_b16 v[134:135], v163 offset:11616
	v_mfma_f32_16x16x32_bf16 v[68:71], v[136:139], v[88:91], v[68:71]
	v_mfma_f32_16x16x32_bf16 v[72:75], v[140:143], v[88:91], v[72:75]
	v_mfma_f32_16x16x32_bf16 v[76:79], v[144:147], v[88:91], v[76:79]
	v_mfma_f32_16x16x32_bf16 v[80:83], v[148:151], v[88:91], v[80:83]
	s_waitcnt lgkmcnt(0)
	ds_read_b64_tr_b16 v[136:137], v163 offset:13824
	ds_read_b64_tr_b16 v[138:139], v163 offset:16128
	ds_read_b64_tr_b16 v[140:141], v163 offset:13856
	ds_read_b64_tr_b16 v[142:143], v163 offset:16160
	ds_read_b64_tr_b16 v[144:145], v163 offset:13888
	ds_read_b64_tr_b16 v[146:147], v163 offset:16192
	ds_read_b64_tr_b16 v[148:149], v163 offset:13920
	ds_read_b64_tr_b16 v[150:151], v163 offset:16224
	v_mfma_f32_16x16x32_bf16 v[68:71], v[120:123], v[92:95], v[68:71]
	v_mfma_f32_16x16x32_bf16 v[72:75], v[124:127], v[92:95], v[72:75]
	v_mfma_f32_16x16x32_bf16 v[76:79], v[128:131], v[92:95], v[76:79]
	v_mfma_f32_16x16x32_bf16 v[80:83], v[132:135], v[92:95], v[80:83]
	s_waitcnt lgkmcnt(0)
	ds_read_b64_tr_b16 v[120:121], v163 offset:18432
	ds_read_b64_tr_b16 v[122:123], v163 offset:20736
	ds_read_b64_tr_b16 v[124:125], v163 offset:18464
	ds_read_b64_tr_b16 v[126:127], v163 offset:20768
	ds_read_b64_tr_b16 v[128:129], v163 offset:18496
	ds_read_b64_tr_b16 v[130:131], v163 offset:20800
	ds_read_b64_tr_b16 v[132:133], v163 offset:18528
	ds_read_b64_tr_b16 v[134:135], v163 offset:20832
	v_mfma_f32_16x16x32_bf16 v[68:71], v[136:139], v[96:99], v[68:71]
	v_mfma_f32_16x16x32_bf16 v[72:75], v[140:143], v[96:99], v[72:75]
	v_mfma_f32_16x16x32_bf16 v[76:79], v[144:147], v[96:99], v[76:79]
	v_mfma_f32_16x16x32_bf16 v[80:83], v[148:151], v[96:99], v[80:83]
	s_waitcnt lgkmcnt(0)
	v_mfma_f32_16x16x32_bf16 v[68:71], v[120:123], v[100:103], v[68:71]
	v_mfma_f32_16x16x32_bf16 v[72:75], v[124:127], v[100:103], v[72:75]
	v_mfma_f32_16x16x32_bf16 v[76:79], v[128:131], v[100:103], v[76:79]
	v_mfma_f32_16x16x32_bf16 v[80:83], v[132:135], v[100:103], v[80:83]
	v_rcp_f32_e32 v172, v171
	s_nop 7
	s_nop 3
	v_mul_f32_e32 v68, v68, v172
	v_mul_f32_e32 v69, v69, v172
	v_mul_f32_e32 v70, v70, v172
	v_mul_f32_e32 v71, v71, v172
	v_mul_f32_e32 v171, v68, v68
	v_fmac_f32_e32 v171, v69, v69
	v_fmac_f32_e32 v171, v70, v70
	v_fmac_f32_e32 v171, v71, v71
	v_cvt_pk_bf16_f32 v180, v68, v69
	v_cvt_pk_bf16_f32 v181, v70, v71
	global_store_dwordx2 v165, v[180:181], s[10:11] offset:128
	v_mul_f32_e32 v72, v72, v172
	v_mul_f32_e32 v73, v73, v172
	v_mul_f32_e32 v74, v74, v172
	v_mul_f32_e32 v75, v75, v172
	v_fmac_f32_e32 v171, v72, v72
	v_fmac_f32_e32 v171, v73, v73
	v_fmac_f32_e32 v171, v74, v74
	v_fmac_f32_e32 v171, v75, v75
	v_cvt_pk_bf16_f32 v180, v72, v73
	v_cvt_pk_bf16_f32 v181, v74, v75
	global_store_dwordx2 v165, v[180:181], s[10:11] offset:160
	v_mul_f32_e32 v76, v76, v172
	v_mul_f32_e32 v77, v77, v172
	v_mul_f32_e32 v78, v78, v172
	v_mul_f32_e32 v79, v79, v172
	v_fmac_f32_e32 v171, v76, v76
	v_fmac_f32_e32 v171, v77, v77
	v_fmac_f32_e32 v171, v78, v78
	v_fmac_f32_e32 v171, v79, v79
	v_cvt_pk_bf16_f32 v180, v76, v77
	v_cvt_pk_bf16_f32 v181, v78, v79
	global_store_dwordx2 v165, v[180:181], s[10:11] offset:192
	v_mul_f32_e32 v80, v80, v172
	v_mul_f32_e32 v81, v81, v172
	v_mul_f32_e32 v82, v82, v172
	v_mul_f32_e32 v83, v83, v172
	v_fmac_f32_e32 v171, v80, v80
	v_fmac_f32_e32 v171, v81, v81
	v_fmac_f32_e32 v171, v82, v82
	v_fmac_f32_e32 v171, v83, v83
	v_cvt_pk_bf16_f32 v180, v80, v81
	v_cvt_pk_bf16_f32 v181, v82, v83
	global_store_dwordx2 v165, v[180:181], s[10:11] offset:224
	ds_bpermute_b32 v177, v173, v171
	s_waitcnt lgkmcnt(0)
	v_add_f32_e32 v171, v171, v177
	ds_bpermute_b32 v177, v174, v171
	s_waitcnt lgkmcnt(0)
	v_add_f32_e32 v171, v171, v177
	s_mov_b64 exec, s[48:49]
	global_store_dword v166, v171, s[30:31]
	s_mov_b64 exec, -1
	s_cmp_eq_u32 s28, 0
	s_cbranch_scc1 .Lm1b_st1_first
	global_load_dwordx4 v[120:123], v167, s[18:19] offset:128
	global_load_dwordx4 v[124:127], v167, s[18:19] offset:384
	global_load_dwordx4 v[128:131], v167, s[20:21] offset:128
	global_load_dwordx4 v[132:135], v167, s[20:21] offset:384
	global_load_dwordx4 v[136:139], v167, s[22:23] offset:128
	global_load_dwordx4 v[140:143], v167, s[22:23] offset:384
	global_load_dwordx4 v[144:147], v167, s[24:25] offset:128
	global_load_dwordx4 v[148:151], v167, s[24:25] offset:384
	s_branch .Lm1b_st1_ld
; #define LAS __attribute__((address_space(3)))
; __global__ void __launch_bounds__(512, 2) fwd_megakernel(Args args) {
;     ...
;                 for (int kvh = 0; kvh < 2; ++kvh) {
;                     if (kvh) __syncthreads();
;                     {
;                         u32x4 kq[4], vq[4];
; #pragma unroll
;                         for (int k = 0; k < 4; ++k) {
;                             const int it = tid + 512 * k, j = it >> 3, d8 = (it & 7) * 8;
;                             kq[k] = (u32x4){0u, 0u, 0u, 0u}; vq[k] = (u32x4){0u, 0u, 0u, 0u};
;                             if (nb > 0 || j >= 128) { const bf16* src = proj + (grow0 + j - 128) * NPROJ + kvh * 64 + d8; kq[k] = *(const u32x4*)(src + PC_K); vq[k] = *(const u32x4*)(src + PC_V); }
;                         }
; #pragma unroll
;                         for (int k = 0; k < 4; ++k) {
;                             const int it = tid + 512 * k, j = it >> 3, d8 = (it & 7) * 8;
;                             *(LAS u32x4*)(Ks + j * 72 + d8) = kq[k];
;                             const unsigned vw[4] = {vq[k].x, vq[k].y, vq[k].z, vq[k].w};
; #pragma unroll
;                             for (int i = 0; i < 4; ++i) { VT[(d8 + 2 * i) * 280 + j] = (bf16)(vw[i] & 0xffffu); VT[(d8 + 2 * i + 1) * 280 + j] = (bf16)(vw[i] >> 16); }
;                         }
;                     }
;                     __syncthreads();
; #pragma unroll
;                     for (int g = 0; g < 2; ++g) {
;                         const int hq = kvh * 2 + g;
;                         const float sink = args.in[13][layer * 4 + hq];
;                         const bf16* qp = proj + (grow0 + 16 * wave + r16) * NPROJ + PC_Q + hq * 64 + q4 * 8;
;                         const bf16x8 aq0 = *(const bf16x8*)qp, aq1 = *(const bf16x8*)(qp + 32);
;                         f32x4 sc[9];
; #pragma unroll
;                         for (int kk = 0; kk < 9; ++kk) {
;                             const int krow = 16 * (wave + kk) + r16;
;                             f32x4 a = (f32x4){0.f, 0.f, 0.f, 0.f};
;                             a = mfma16(aq0, lds_frag(Ks, krow, 72, q4 * 8), a);
;                             a = mfma16(aq1, lds_frag(Ks, krow, 72, 32 + q4 * 8), a);
;                             sc[kk] = a;
;                         }
;                         float sm[4];
; #pragma unroll
;                         for (int j = 0; j < 4; ++j) {
.Lm1b_st1_first:
	v_mov_b32_e32 v120, 0
	v_mov_b32_e32 v121, 0
	v_mov_b32_e32 v122, 0
	v_mov_b32_e32 v123, 0
	v_mov_b32_e32 v124, 0
	v_mov_b32_e32 v125, 0
	v_mov_b32_e32 v126, 0
	v_mov_b32_e32 v127, 0
	v_mov_b32_e32 v128, 0
	v_mov_b32_e32 v129, 0
	v_mov_b32_e32 v130, 0
	v_mov_b32_e32 v131, 0
	v_mov_b32_e32 v132, 0
	v_mov_b32_e32 v133, 0
	v_mov_b32_e32 v134, 0
	v_mov_b32_e32 v135, 0
	global_load_dwordx4 v[136:139], v167, s[22:23] offset:128
	global_load_dwordx4 v[140:143], v167, s[22:23] offset:384
	global_load_dwordx4 v[144:147], v167, s[24:25] offset:128
	global_load_dwordx4 v[148:151], v167, s[24:25] offset:384
.Lm1b_st1_ld:
	s_barrier
	s_waitcnt vmcnt(0)
	ds_write_b128 v168, v[120:123] offset:0
	ds_write_b128 v168, v[124:127] offset:36864
	ds_write_b128 v168, v[128:131] offset:9216
	ds_write_b128 v168, v[132:135] offset:46080
	ds_write_b128 v168, v[136:139] offset:18432
	ds_write_b128 v168, v[140:143] offset:55296
	ds_write_b128 v168, v[144:147] offset:27648
	ds_write_b128 v168, v[148:151] offset:64512
	s_waitcnt lgkmcnt(0)
	s_barrier
	s_add_u32 s30, s12, 262144
	s_addc_u32 s31, s13, 0
	v_add_u32_e32 v175, 1024, v164
	ds_read_b128 v[104:107], v162 offset:0
	ds_read_b128 v[108:111], v162 offset:64
	ds_read_b128 v[112:115], v162 offset:2304
	ds_read_b128 v[116:119], v162 offset:2368
	s_waitcnt lgkmcnt(2)
	v_mfma_f32_16x16x32_bf16 v[32:35], v[104:107], v[16:19], 0
	v_mfma_f32_16x16x32_bf16 v[32:35], v[108:111], v[20:23], v[32:35]
	ds_read_b128 v[104:107], v162 offset:4608
	ds_read_b128 v[108:111], v162 offset:4672
	s_waitcnt lgkmcnt(2)
	v_mfma_f32_16x16x32_bf16 v[36:39], v[112:115], v[16:19], 0
	v_mfma_f32_16x16x32_bf16 v[36:39], v[116:119], v[20:23], v[36:39]
	ds_read_b128 v[112:115], v162 offset:6912
	ds_read_b128 v[116:119], v162 offset:6976
	s_waitcnt lgkmcnt(2)
	v_mfma_f32_16x16x32_bf16 v[40:43], v[104:107], v[16:19], 0
	v_mfma_f32_16x16x32_bf16 v[40:43], v[108:111], v[20:23], v[40:43]
	ds_read_b128 v[104:107], v162 offset:9216
	ds_read_b128 v[108:111], v162 offset:9280
	s_waitcnt lgkmcnt(2)
	v_mfma_f32_16x16x32_bf16 v[44:47], v[112:115], v[16:19], 0
	v_mfma_f32_16x16x32_bf16 v[44:47], v[116:119], v[20:23], v[44:47]
	ds_read_b128 v[112:115], v162 offset:11520
	ds_read_b128 v[116:119], v162 offset:11584
	s_waitcnt lgkmcnt(2)
	v_mfma_f32_16x16x32_bf16 v[48:51], v[104:107], v[16:19], 0
	v_mfma_f32_16x16x32_bf16 v[48:51], v[108:111], v[20:23], v[48:51]
	ds_read_b128 v[104:107], v162 offset:13824
	ds_read_b128 v[108:111], v162 offset:13888
	s_waitcnt lgkmcnt(2)
	v_mfma_f32_16x16x32_bf16 v[52:55], v[112:115], v[16:19], 0
	v_mfma_f32_16x16x32_bf16 v[52:55], v[116:119], v[20:23], v[52:55]
	ds_read_b128 v[112:115], v162 offset:16128
	ds_read_b128 v[116:119], v162 offset:16192
	s_waitcnt lgkmcnt(2)
	v_mfma_f32_16x16x32_bf16 v[56:59], v[104:107], v[16:19], 0
	v_mfma_f32_16x16x32_bf16 v[56:59], v[108:111], v[20:23], v[56:59]
	ds_read_b128 v[104:107], v162 offset:18432
	ds_read_b128 v[108:111], v162 offset:18496
	s_waitcnt lgkmcnt(2)
	v_mfma_f32_16x16x32_bf16 v[60:63], v[112:115], v[16:19], 0
	v_mfma_f32_16x16x32_bf16 v[60:63], v[116:119], v[20:23], v[60:63]
	s_waitcnt lgkmcnt(0)
	v_mfma_f32_16x16x32_bf16 v[64:67], v[104:107], v[16:19], 0
	v_mfma_f32_16x16x32_bf16 v[64:67], v[108:111], v[20:23], v[64:67]
	ds_read2_b32 v[122:123], v175 offset0:128 offset1:129
	ds_read2_b32 v[120:121], v175 offset0:130 offset1:131
	ds_read2_b32 v[126:127], v175 offset0:112 offset1:113
	ds_read2_b32 v[124:125], v175 offset0:114 offset1:115
	ds_read2_b32 v[130:131], v175 offset0:96 offset1:97
	ds_read2_b32 v[128:129], v175 offset0:98 offset1:99
	ds_read2_b32 v[134:135], v175 offset0:80 offset1:81
	ds_read2_b32 v[132:133], v175 offset0:82 offset1:83
	ds_read2_b32 v[138:139], v175 offset0:64 offset1:65
	ds_read2_b32 v[136:137], v175 offset0:66 offset1:67
	ds_read2_b32 v[142:143], v175 offset0:48 offset1:49
	ds_read2_b32 v[140:141], v175 offset0:50 offset1:51
	ds_read2_b32 v[146:147], v175 offset0:32 offset1:33
	ds_read2_b32 v[144:145], v175 offset0:34 offset1:35
	ds_read2_b32 v[150:151], v175 offset0:16 offset1:17
	ds_read2_b32 v[148:149], v175 offset0:18 offset1:19
	ds_read2_b32 v[154:155], v175 offset0:0 offset1:1
	ds_read2_b32 v[152:153], v175 offset0:2 offset1:3
	s_waitcnt lgkmcnt(0)
	s_nop 4
	v_fma_f32 v32, v32, s50, v121
	v_fma_f32 v33, v33, s50, v120
	v_fma_f32 v34, v34, s50, v123
	v_fma_f32 v35, v35, s50, v122
	v_fma_f32 v36, v36, s50, v125
	v_fma_f32 v37, v37, s50, v124
	v_fma_f32 v38, v38, s50, v127
	v_fma_f32 v39, v39, s50, v126
	v_fma_f32 v40, v40, s50, v129
	v_fma_f32 v41, v41, s50, v128
	v_fma_f32 v42, v42, s50, v131
	v_fma_f32 v43, v43, s50, v130
	v_fma_f32 v44, v44, s50, v133
	v_fma_f32 v45, v45, s50, v132
	v_fma_f32 v46, v46, s50, v135
	v_fma_f32 v47, v47, s50, v134
	v_fma_f32 v48, v48, s50, v137
	v_fma_f32 v49, v49, s50, v136
	v_fma_f32 v50, v50, s50, v139
	v_fma_f32 v51, v51, s50, v138
	v_fma_f32 v52, v52, s50, v141
	v_fma_f32 v53, v53, s50, v140
	v_fma_f32 v54, v54, s50, v143
	v_fma_f32 v55, v55, s50, v142
	v_fma_f32 v56, v56, s50, v145
	v_fma_f32 v57, v57, s50, v144
	v_fma_f32 v58, v58, s50, v147
	v_fma_f32 v59, v59, s50, v146
	v_fma_f32 v60, v60, s50, v149
	v_fma_f32 v61, v61, s50, v148
	v_fma_f32 v62, v62, s50, v151
	v_fma_f32 v63, v63, s50, v150
	v_fma_f32 v64, v64, s50, v153
	v_fma_f32 v65, v65, s50, v152
	v_fma_f32 v66, v66, s50, v155
	v_fma_f32 v67, v67, s50, v154
	v_mov_b32_e32 v176, 0xff800000
	v_cndmask_b32_e64 v32, v32, v176, s[40:41]
	v_cndmask_b32_e64 v64, v176, v64, s[40:41]
	v_cndmask_b32_e64 v33, v33, v176, s[42:43]
	v_cndmask_b32_e64 v65, v176, v65, s[42:43]
	v_cndmask_b32_e64 v34, v34, v176, s[44:45]
	v_cndmask_b32_e64 v66, v176, v66, s[44:45]
	v_cndmask_b32_e64 v35, v35, v176, s[46:47]
	v_cndmask_b32_e64 v67, v176, v67, s[46:47]
	s_cmp_lt_u32 0, s29
	s_cbranch_scc0 .Lm1b_h2_nomask
; #define LAS __attribute__((address_space(3)))
; DI unsigned short f2bf(float f) { return (unsigned short)(pk2(f, 0.f) & 0xffffu); }
; DI float sum16(float v) { v += __shfl_xor(v, 1); v += __shfl_xor(v, 2); v += __shfl_xor(v, 4); v += __shfl_xor(v, 8); return v; }
; DI float max16(float v) { v = fmaxf(v, __shfl_xor(v, 1)); v = fmaxf(v, __shfl_xor(v, 2)); v = fmaxf(v, __shfl_xor(v, 4)); v = fmaxf(v, __shfl_xor(v, 8)); return v; }
; __global__ void __launch_bounds__(512, 2) fwd_megakernel(Args args) {
;     ...
;                                 const bool ok = (dist >= 0) && (dist < 128) && (nb > 0 || jk >= 128);
;                                 const float sv = ok ? sc[kk][j] * 0.125f + s_bias[hq * 128 + (dist & 127)] : -INFINITY;
;                                 sc[kk][j] = sv; m = fmaxf(m, sv);
;                             }
;                             m = fmaxf(max16(m), sink);
;                             float su = 0.f;
; #pragma unroll
;                             for (int kk = 0; kk < 9; ++kk) { const float p = __expf(sc[kk][j] - m); sc[kk][j] = p; su += p; }
;                             sm[j] = sum16(su) + __expf(sink - m);
;                         }
; #pragma unroll
;                         for (int kk = 0; kk < 9; ++kk)
; #pragma unroll
;                             for (int j = 0; j < 4; ++j) Ps[(q4 * 4 + j) * 168 + kk * 16 + r16] = f2bf(sc[kk][j]);
;                         *(LAS u32x2*)(Ps + (lane >> 2) * 168 + 144 + (lane & 3) * 4) = (u32x2){0u, 0u};
	v_mov_b32_e32 v32, 0xff800000
	v_mov_b32_e32 v33, 0xff800000
	v_mov_b32_e32 v34, 0xff800000
	v_mov_b32_e32 v35, 0xff800000
	s_cmp_lt_u32 1, s29
	s_cbranch_scc0 .Lm1b_h2_nomask
	v_mov_b32_e32 v36, 0xff800000
	v_mov_b32_e32 v37, 0xff800000
	v_mov_b32_e32 v38, 0xff800000
	v_mov_b32_e32 v39, 0xff800000
	s_cmp_lt_u32 2, s29
	s_cbranch_scc0 .Lm1b_h2_nomask
	v_mov_b32_e32 v40, 0xff800000
	v_mov_b32_e32 v41, 0xff800000
	v_mov_b32_e32 v42, 0xff800000
	v_mov_b32_e32 v43, 0xff800000
	s_cmp_lt_u32 3, s29
	s_cbranch_scc0 .Lm1b_h2_nomask
	v_mov_b32_e32 v44, 0xff800000
	v_mov_b32_e32 v45, 0xff800000
	v_mov_b32_e32 v46, 0xff800000
	v_mov_b32_e32 v47, 0xff800000
	s_cmp_lt_u32 4, s29
	s_cbranch_scc0 .Lm1b_h2_nomask
	v_mov_b32_e32 v48, 0xff800000
	v_mov_b32_e32 v49, 0xff800000
	v_mov_b32_e32 v50, 0xff800000
	v_mov_b32_e32 v51, 0xff800000
	s_cmp_lt_u32 5, s29
	s_cbranch_scc0 .Lm1b_h2_nomask
	v_mov_b32_e32 v52, 0xff800000
	v_mov_b32_e32 v53, 0xff800000
	v_mov_b32_e32 v54, 0xff800000
	v_mov_b32_e32 v55, 0xff800000
	s_cmp_lt_u32 6, s29
	s_cbranch_scc0 .Lm1b_h2_nomask
	v_mov_b32_e32 v56, 0xff800000
	v_mov_b32_e32 v57, 0xff800000
	v_mov_b32_e32 v58, 0xff800000
	v_mov_b32_e32 v59, 0xff800000
	s_cmp_lt_u32 7, s29
	s_cbranch_scc0 .Lm1b_h2_nomask
	v_mov_b32_e32 v60, 0xff800000
	v_mov_b32_e32 v61, 0xff800000
	v_mov_b32_e32 v62, 0xff800000
	v_mov_b32_e32 v63, 0xff800000
.Lm1b_h2_nomask:
	v_max3_f32 v170, v32, v33, v34
	v_max3_f32 v170, v170, v35, v36
	v_max3_f32 v170, v170, v37, v38
	v_max3_f32 v170, v170, v39, v40
	v_max3_f32 v170, v170, v41, v42
	v_max3_f32 v170, v170, v43, v44
	v_max3_f32 v170, v170, v45, v46
	v_max3_f32 v170, v170, v47, v48
	v_max3_f32 v170, v170, v49, v50
	v_max3_f32 v170, v170, v51, v52
	v_max3_f32 v170, v170, v53, v54
	v_max3_f32 v170, v170, v55, v56
	v_max3_f32 v170, v170, v57, v58
	v_max3_f32 v170, v170, v59, v60
	v_max3_f32 v170, v170, v61, v62
	v_max3_f32 v170, v170, v63, v64
	v_max3_f32 v170, v170, v65, v66
	v_max_f32_e32 v170, v170, v67
	ds_bpermute_b32 v177, v173, v170
	s_waitcnt lgkmcnt(0)
	v_max_f32_e32 v170, v170, v177
	ds_bpermute_b32 v177, v174, v170
	s_waitcnt lgkmcnt(0)
	v_max_f32_e32 v170, v170, v177
	v_max_f32_e32 v170, s38, v170
	v_mul_f32_e32 v178, 0x3fb8aa3b, v170
	v_fma_f32 v32, v32, v179, -v178
	v_fma_f32 v33, v33, v179, -v178
	v_fma_f32 v34, v34, v179, -v178
	v_fma_f32 v35, v35, v179, -v178
	v_fma_f32 v36, v36, v179, -v178
	v_fma_f32 v37, v37, v179, -v178
	v_fma_f32 v38, v38, v179, -v178
	v_fma_f32 v39, v39, v179, -v178
	v_fma_f32 v40, v40, v179, -v178
	v_fma_f32 v41, v41, v179, -v178
	v_fma_f32 v42, v42, v179, -v178
	v_fma_f32 v43, v43, v179, -v178
	v_fma_f32 v44, v44, v179, -v178
	v_fma_f32 v45, v45, v179, -v178
	v_fma_f32 v46, v46, v179, -v178
	v_fma_f32 v47, v47, v179, -v178
	v_fma_f32 v48, v48, v179, -v178
	v_fma_f32 v49, v49, v179, -v178
	v_fma_f32 v50, v50, v179, -v178
	v_fma_f32 v51, v51, v179, -v178
	v_fma_f32 v52, v52, v179, -v178
	v_fma_f32 v53, v53, v179, -v178
	v_fma_f32 v54, v54, v179, -v178
	v_fma_f32 v55, v55, v179, -v178
	v_fma_f32 v56, v56, v179, -v178
	v_fma_f32 v57, v57, v179, -v178
	v_fma_f32 v58, v58, v179, -v178
	v_fma_f32 v59, v59, v179, -v178
	v_fma_f32 v60, v60, v179, -v178
	v_fma_f32 v61, v61, v179, -v178
	v_fma_f32 v62, v62, v179, -v178
	v_fma_f32 v63, v63, v179, -v178
	v_fma_f32 v64, v64, v179, -v178
	v_fma_f32 v65, v65, v179, -v178
	v_fma_f32 v66, v66, v179, -v178
	v_fma_f32 v67, v67, v179, -v178
	v_exp_f32_e32 v32, v32
	v_exp_f32_e32 v33, v33
	v_exp_f32_e32 v34, v34
	v_exp_f32_e32 v35, v35
	v_exp_f32_e32 v36, v36
	v_exp_f32_e32 v37, v37
	v_exp_f32_e32 v38, v38
	v_exp_f32_e32 v39, v39
	v_exp_f32_e32 v40, v40
	v_exp_f32_e32 v41, v41
	v_exp_f32_e32 v42, v42
	v_exp_f32_e32 v43, v43
	v_exp_f32_e32 v44, v44
	v_exp_f32_e32 v45, v45
	v_exp_f32_e32 v46, v46
	v_exp_f32_e32 v47, v47
	v_exp_f32_e32 v48, v48
	v_exp_f32_e32 v49, v49
	v_exp_f32_e32 v50, v50
	v_exp_f32_e32 v51, v51
	v_exp_f32_e32 v52, v52
	v_exp_f32_e32 v53, v53
	v_exp_f32_e32 v54, v54
	v_exp_f32_e32 v55, v55
	v_exp_f32_e32 v56, v56
	v_exp_f32_e32 v57, v57
	v_exp_f32_e32 v58, v58
	v_exp_f32_e32 v59, v59
	v_exp_f32_e32 v60, v60
	v_exp_f32_e32 v61, v61
	v_exp_f32_e32 v62, v62
	v_exp_f32_e32 v63, v63
	v_exp_f32_e32 v64, v64
	v_exp_f32_e32 v65, v65
	v_exp_f32_e32 v66, v66
	v_exp_f32_e32 v67, v67
	s_nop 0
	v_add_f32_e32 v180, v32, v36
	v_add_f32_e32 v181, v33, v37
	v_add_f32_e32 v182, v34, v38
	v_add_f32_e32 v183, v35, v39
	v_add_f32_e32 v180, v180, v40
	v_add_f32_e32 v181, v181, v41
	v_add_f32_e32 v182, v182, v42
	v_add_f32_e32 v183, v183, v43
	v_add_f32_e32 v180, v180, v44
	v_add_f32_e32 v181, v181, v45
	v_add_f32_e32 v182, v182, v46
	v_add_f32_e32 v183, v183, v47
	v_add_f32_e32 v180, v180, v48
	v_add_f32_e32 v181, v181, v49
	v_add_f32_e32 v182, v182, v50
	v_add_f32_e32 v183, v183, v51
	v_add_f32_e32 v180, v180, v52
	v_add_f32_e32 v181, v181, v53
	v_add_f32_e32 v182, v182, v54
	v_add_f32_e32 v183, v183, v55
	v_add_f32_e32 v180, v180, v56
	v_add_f32_e32 v181, v181, v57
	v_add_f32_e32 v182, v182, v58
	v_add_f32_e32 v183, v183, v59
	v_add_f32_e32 v180, v180, v60
	v_add_f32_e32 v181, v181, v61
	v_add_f32_e32 v182, v182, v62
	v_add_f32_e32 v183, v183, v63
	v_add_f32_e32 v180, v180, v64
	v_add_f32_e32 v181, v181, v65
	v_add_f32_e32 v182, v182, v66
	v_add_f32_e32 v183, v183, v67
	v_add_f32_e32 v180, v180, v181
	v_add_f32_e32 v182, v182, v183
	v_add_f32_e32 v171, v180, v182
	ds_bpermute_b32 v177, v173, v171
	v_cvt_pk_bf16_f32 v84, v32, v33
	v_cvt_pk_bf16_f32 v85, v34, v35
	v_cvt_pk_bf16_f32 v86, v36, v37
	v_cvt_pk_bf16_f32 v87, v38, v39
	v_cvt_pk_bf16_f32 v88, v40, v41
	v_cvt_pk_bf16_f32 v89, v42, v43
	v_cvt_pk_bf16_f32 v90, v44, v45
	v_cvt_pk_bf16_f32 v91, v46, v47
	v_cvt_pk_bf16_f32 v92, v48, v49
	v_cvt_pk_bf16_f32 v93, v50, v51
	v_cvt_pk_bf16_f32 v94, v52, v53
	v_cvt_pk_bf16_f32 v95, v54, v55
	v_cvt_pk_bf16_f32 v96, v56, v57
	v_cvt_pk_bf16_f32 v97, v58, v59
	v_cvt_pk_bf16_f32 v98, v60, v61
	v_cvt_pk_bf16_f32 v99, v62, v63
	v_cvt_pk_bf16_f32 v100, v64, v65
	v_cvt_pk_bf16_f32 v101, v66, v67
	v_mov_b32_e32 v102, 0
	v_mov_b32_e32 v103, 0
	s_waitcnt lgkmcnt(0)
; #define LAS __attribute__((address_space(3)))
; DI unsigned short f2bf(float f) { return (unsigned short)(pk2(f, 0.f) & 0xffffu); }
; DI float sum16(float v) { v += __shfl_xor(v, 1); v += __shfl_xor(v, 2); v += __shfl_xor(v, 4); v += __shfl_xor(v, 8); return v; }
; DI f32x4 mfma16(bf16x8 a, bf16x8 b, f32x4 c) { return __builtin_amdgcn_mfma_f32_16x16x32_bf16(a, b, c, 0, 0, 0); }
; __global__ void __launch_bounds__(512, 2) fwd_megakernel(Args args) {
;     ...
;                             sm[j] = sum16(su) + __expf(sink - m);
;                         }
; #pragma unroll
;                         for (int kk = 0; kk < 9; ++kk)
; #pragma unroll
;                             for (int j = 0; j < 4; ++j) Ps[(q4 * 4 + j) * 168 + kk * 16 + r16] = f2bf(sc[kk][j]);
;                         *(LAS u32x2*)(Ps + (lane >> 2) * 168 + 144 + (lane & 3) * 4) = (u32x2){0u, 0u};
;                         f32x4 oa[4];
; #pragma unroll
;                         for (int dt = 0; dt < 4; ++dt) oa[dt] = (f32x4){0.f, 0.f, 0.f, 0.f};
; #pragma unroll
;                         for (int ks = 0; ks < 5; ++ks) {
;                             const bf16x8 pa = lds_frag(Ps, r16, 168, ks * 32 + q4 * 8);
; #pragma unroll
;                             for (int dt = 0; dt < 4; ++dt) oa[dt] = mfma16(pa, lds_frag(VT, 16 * dt + r16, 280, 16 * wave + ks * 32 + q4 * 8), oa[dt]);
;                         }
; #pragma unroll
;                         for (int j = 0; j < 4; ++j) { const float inv = 1.f / sm[j];
; #pragma unroll
;                             for (int dt = 0; dt < 4; ++dt) { const float o = oa[dt][j] * inv; ssr[j] += o * o; og[hq][dt][j] = o; } }
;                     }
;                 }
; #pragma unroll
;                 for (int hq = 0; hq < 4; ++hq) {
; #pragma unroll
;                     for (int j = 0; j < 4; ++j) {
;                         const size_t row = grow0 + 16 * wave + q4 * 4 + j; float ss = 0.f;
; #pragma unroll
;                         for (int dt = 0; dt < 4; ++dt) { const float o = og[hq][dt][j]; ss += o * o; Yg[row * DM + 512 + hq * 64 + 16 * dt + r16] = f2bf(o); }
;                         ss = sum16(ss);
;                         if (r16 == 0) mss_a[(size_t)hq * MTOK + row] = ss;
;                     }
	v_add_f32_e32 v171, v171, v177
	ds_bpermute_b32 v177, v174, v171
	v_sub_f32_e32 v176, s38, v170
	v_mul_f32_e32 v176, 0x3fb8aa3b, v176
	v_exp_f32_e32 v176, v176
	ds_read_b64_tr_b16 v[120:121], v163 offset:0
	ds_read_b64_tr_b16 v[122:123], v163 offset:2304
	ds_read_b64_tr_b16 v[124:125], v163 offset:32
	ds_read_b64_tr_b16 v[126:127], v163 offset:2336
	ds_read_b64_tr_b16 v[128:129], v163 offset:64
	ds_read_b64_tr_b16 v[130:131], v163 offset:2368
	ds_read_b64_tr_b16 v[132:133], v163 offset:96
	ds_read_b64_tr_b16 v[134:135], v163 offset:2400
	s_waitcnt lgkmcnt(8)
	v_add_f32_e32 v171, v171, v177
	v_add_f32_e32 v171, v171, v176
	s_waitcnt lgkmcnt(0)
	ds_read_b64_tr_b16 v[136:137], v163 offset:4608
	ds_read_b64_tr_b16 v[138:139], v163 offset:6912
	ds_read_b64_tr_b16 v[140:141], v163 offset:4640
	ds_read_b64_tr_b16 v[142:143], v163 offset:6944
	ds_read_b64_tr_b16 v[144:145], v163 offset:4672
	ds_read_b64_tr_b16 v[146:147], v163 offset:6976
	ds_read_b64_tr_b16 v[148:149], v163 offset:4704
	ds_read_b64_tr_b16 v[150:151], v163 offset:7008
	v_mfma_f32_16x16x32_bf16 v[68:71], v[120:123], v[84:87], 0
	v_mfma_f32_16x16x32_bf16 v[72:75], v[124:127], v[84:87], 0
	v_mfma_f32_16x16x32_bf16 v[76:79], v[128:131], v[84:87], 0
	v_mfma_f32_16x16x32_bf16 v[80:83], v[132:135], v[84:87], 0
	s_waitcnt lgkmcnt(0)
	ds_read_b64_tr_b16 v[120:121], v163 offset:9216
	ds_read_b64_tr_b16 v[122:123], v163 offset:11520
	ds_read_b64_tr_b16 v[124:125], v163 offset:9248
	ds_read_b64_tr_b16 v[126:127], v163 offset:11552
	ds_read_b64_tr_b16 v[128:129], v163 offset:9280
	ds_read_b64_tr_b16 v[130:131], v163 offset:11584
	ds_read_b64_tr_b16 v[132:133], v163 offset:9312
	ds_read_b64_tr_b16 v[134:135], v163 offset:11616
	v_mfma_f32_16x16x32_bf16 v[68:71], v[136:139], v[88:91], v[68:71]
	v_mfma_f32_16x16x32_bf16 v[72:75], v[140:143], v[88:91], v[72:75]
	v_mfma_f32_16x16x32_bf16 v[76:79], v[144:147], v[88:91], v[76:79]
	v_mfma_f32_16x16x32_bf16 v[80:83], v[148:151], v[88:91], v[80:83]
	s_waitcnt lgkmcnt(0)
	ds_read_b64_tr_b16 v[136:137], v163 offset:13824
	ds_read_b64_tr_b16 v[138:139], v163 offset:16128
	ds_read_b64_tr_b16 v[140:141], v163 offset:13856
	ds_read_b64_tr_b16 v[142:143], v163 offset:16160
	ds_read_b64_tr_b16 v[144:145], v163 offset:13888
	ds_read_b64_tr_b16 v[146:147], v163 offset:16192
	ds_read_b64_tr_b16 v[148:149], v163 offset:13920
	ds_read_b64_tr_b16 v[150:151], v163 offset:16224
	v_mfma_f32_16x16x32_bf16 v[68:71], v[120:123], v[92:95], v[68:71]
	v_mfma_f32_16x16x32_bf16 v[72:75], v[124:127], v[92:95], v[72:75]
	v_mfma_f32_16x16x32_bf16 v[76:79], v[128:131], v[92:95], v[76:79]
	v_mfma_f32_16x16x32_bf16 v[80:83], v[132:135], v[92:95], v[80:83]
	s_waitcnt lgkmcnt(0)
	ds_read_b64_tr_b16 v[120:121], v163 offset:18432
	ds_read_b64_tr_b16 v[122:123], v163 offset:20736
	ds_read_b64_tr_b16 v[124:125], v163 offset:18464
	ds_read_b64_tr_b16 v[126:127], v163 offset:20768
	ds_read_b64_tr_b16 v[128:129], v163 offset:18496
	ds_read_b64_tr_b16 v[130:131], v163 offset:20800
	ds_read_b64_tr_b16 v[132:133], v163 offset:18528
	ds_read_b64_tr_b16 v[134:135], v163 offset:20832
	v_mfma_f32_16x16x32_bf16 v[68:71], v[136:139], v[96:99], v[68:71]
	v_mfma_f32_16x16x32_bf16 v[72:75], v[140:143], v[96:99], v[72:75]
	v_mfma_f32_16x16x32_bf16 v[76:79], v[144:147], v[96:99], v[76:79]
	v_mfma_f32_16x16x32_bf16 v[80:83], v[148:151], v[96:99], v[80:83]
	s_waitcnt lgkmcnt(0)
	v_mfma_f32_16x16x32_bf16 v[68:71], v[120:123], v[100:103], v[68:71]
	v_mfma_f32_16x16x32_bf16 v[72:75], v[124:127], v[100:103], v[72:75]
	v_mfma_f32_16x16x32_bf16 v[76:79], v[128:131], v[100:103], v[76:79]
	v_mfma_f32_16x16x32_bf16 v[80:83], v[132:135], v[100:103], v[80:83]
	v_rcp_f32_e32 v172, v171
	s_nop 7
	s_nop 3
	v_mul_f32_e32 v68, v68, v172
	v_mul_f32_e32 v69, v69, v172
	v_mul_f32_e32 v70, v70, v172
	v_mul_f32_e32 v71, v71, v172
	v_mul_f32_e32 v171, v68, v68
	v_fmac_f32_e32 v171, v69, v69
	v_fmac_f32_e32 v171, v70, v70
	v_fmac_f32_e32 v171, v71, v71
	v_cvt_pk_bf16_f32 v180, v68, v69
	v_cvt_pk_bf16_f32 v181, v70, v71
	global_store_dwordx2 v165, v[180:181], s[10:11] offset:256
	v_mul_f32_e32 v72, v72, v172
	v_mul_f32_e32 v73, v73, v172
	v_mul_f32_e32 v74, v74, v172
	v_mul_f32_e32 v75, v75, v172
	v_fmac_f32_e32 v171, v72, v72
	v_fmac_f32_e32 v171, v73, v73
	v_fmac_f32_e32 v171, v74, v74
	v_fmac_f32_e32 v171, v75, v75
	v_cvt_pk_bf16_f32 v180, v72, v73
	v_cvt_pk_bf16_f32 v181, v74, v75
	global_store_dwordx2 v165, v[180:181], s[10:11] offset:288
	v_mul_f32_e32 v76, v76, v172
	v_mul_f32_e32 v77, v77, v172
	v_mul_f32_e32 v78, v78, v172
	v_mul_f32_e32 v79, v79, v172
	v_fmac_f32_e32 v171, v76, v76
	v_fmac_f32_e32 v171, v77, v77
	v_fmac_f32_e32 v171, v78, v78
	v_fmac_f32_e32 v171, v79, v79
	v_cvt_pk_bf16_f32 v180, v76, v77
	v_cvt_pk_bf16_f32 v181, v78, v79
	global_store_dwordx2 v165, v[180:181], s[10:11] offset:320
	v_mul_f32_e32 v80, v80, v172
	v_mul_f32_e32 v81, v81, v172
	v_mul_f32_e32 v82, v82, v172
	v_mul_f32_e32 v83, v83, v172
	v_fmac_f32_e32 v171, v80, v80
	v_fmac_f32_e32 v171, v81, v81
	v_fmac_f32_e32 v171, v82, v82
	v_fmac_f32_e32 v171, v83, v83
	v_cvt_pk_bf16_f32 v180, v80, v81
	v_cvt_pk_bf16_f32 v181, v82, v83
	global_store_dwordx2 v165, v[180:181], s[10:11] offset:352
	ds_bpermute_b32 v177, v173, v171
	s_waitcnt lgkmcnt(0)
	v_add_f32_e32 v171, v171, v177
	ds_bpermute_b32 v177, v174, v171
	s_waitcnt lgkmcnt(0)
	v_add_f32_e32 v171, v171, v177
	s_mov_b64 exec, s[48:49]
	global_store_dword v166, v171, s[30:31]
	s_mov_b64 exec, -1
	s_add_u32 s30, s12, 393216
	s_addc_u32 s31, s13, 0
	v_add_u32_e32 v175, 1536, v164
	ds_read_b128 v[104:107], v162 offset:0
	ds_read_b128 v[108:111], v162 offset:64
	ds_read_b128 v[112:115], v162 offset:2304
	ds_read_b128 v[116:119], v162 offset:2368
	s_waitcnt lgkmcnt(2)
; DI f32x4 mfma16(bf16x8 a, bf16x8 b, f32x4 c) { return __builtin_amdgcn_mfma_f32_16x16x32_bf16(a, b, c, 0, 0, 0); }
; __global__ void __launch_bounds__(512, 2) fwd_megakernel(Args args) {
;     ...
;                         f32x4 sc[9];
; #pragma unroll
;                         for (int kk = 0; kk < 9; ++kk) {
;                             const int krow = 16 * (wave + kk) + r16;
;                             f32x4 a = (f32x4){0.f, 0.f, 0.f, 0.f};
;                             a = mfma16(aq0, lds_frag(Ks, krow, 72, q4 * 8), a);
;                             a = mfma16(aq1, lds_frag(Ks, krow, 72, 32 + q4 * 8), a);
;                             sc[kk] = a;
;                         }
;                         float sm[4];
; #pragma unroll
;                         for (int j = 0; j < 4; ++j) {
;                             const int i = 16 * wave + q4 * 4 + j; float m = -INFINITY;
; #pragma unroll
;                             for (int kk = 0; kk < 9; ++kk) {
;                                 const int jk = 16 * (wave + kk) + r16, dist = i - jk + 128;
;                                 const bool ok = (dist >= 0) && (dist < 128) && (nb > 0 || jk >= 128);
;                                 const float sv = ok ? sc[kk][j] * 0.125f + s_bias[hq * 128 + (dist & 127)] : -INFINITY;
;                                 sc[kk][j] = sv; m = fmaxf(m, sv);
;                             }
	v_mfma_f32_16x16x32_bf16 v[32:35], v[104:107], v[24:27], 0
	v_mfma_f32_16x16x32_bf16 v[32:35], v[108:111], v[28:31], v[32:35]
	ds_read_b128 v[104:107], v162 offset:4608
	ds_read_b128 v[108:111], v162 offset:4672
	s_waitcnt lgkmcnt(2)
	v_mfma_f32_16x16x32_bf16 v[36:39], v[112:115], v[24:27], 0
	v_mfma_f32_16x16x32_bf16 v[36:39], v[116:119], v[28:31], v[36:39]
	ds_read_b128 v[112:115], v162 offset:6912
	ds_read_b128 v[116:119], v162 offset:6976
	s_waitcnt lgkmcnt(2)
	v_mfma_f32_16x16x32_bf16 v[40:43], v[104:107], v[24:27], 0
	v_mfma_f32_16x16x32_bf16 v[40:43], v[108:111], v[28:31], v[40:43]
	ds_read_b128 v[104:107], v162 offset:9216
	ds_read_b128 v[108:111], v162 offset:9280
	s_waitcnt lgkmcnt(2)
	v_mfma_f32_16x16x32_bf16 v[44:47], v[112:115], v[24:27], 0
	v_mfma_f32_16x16x32_bf16 v[44:47], v[116:119], v[28:31], v[44:47]
	ds_read_b128 v[112:115], v162 offset:11520
	ds_read_b128 v[116:119], v162 offset:11584
	s_waitcnt lgkmcnt(2)
	v_mfma_f32_16x16x32_bf16 v[48:51], v[104:107], v[24:27], 0
	v_mfma_f32_16x16x32_bf16 v[48:51], v[108:111], v[28:31], v[48:51]
	ds_read_b128 v[104:107], v162 offset:13824
	ds_read_b128 v[108:111], v162 offset:13888
	s_waitcnt lgkmcnt(2)
	v_mfma_f32_16x16x32_bf16 v[52:55], v[112:115], v[24:27], 0
	v_mfma_f32_16x16x32_bf16 v[52:55], v[116:119], v[28:31], v[52:55]
	ds_read_b128 v[112:115], v162 offset:16128
	ds_read_b128 v[116:119], v162 offset:16192
	s_waitcnt lgkmcnt(2)
	v_mfma_f32_16x16x32_bf16 v[56:59], v[104:107], v[24:27], 0
	v_mfma_f32_16x16x32_bf16 v[56:59], v[108:111], v[28:31], v[56:59]
	ds_read_b128 v[104:107], v162 offset:18432
	ds_read_b128 v[108:111], v162 offset:18496
	s_waitcnt lgkmcnt(2)
	v_mfma_f32_16x16x32_bf16 v[60:63], v[112:115], v[24:27], 0
	v_mfma_f32_16x16x32_bf16 v[60:63], v[116:119], v[28:31], v[60:63]
	s_waitcnt lgkmcnt(0)
	v_mfma_f32_16x16x32_bf16 v[64:67], v[104:107], v[24:27], 0
	v_mfma_f32_16x16x32_bf16 v[64:67], v[108:111], v[28:31], v[64:67]
	ds_read2_b32 v[122:123], v175 offset0:128 offset1:129
	ds_read2_b32 v[120:121], v175 offset0:130 offset1:131
	ds_read2_b32 v[126:127], v175 offset0:112 offset1:113
	ds_read2_b32 v[124:125], v175 offset0:114 offset1:115
	ds_read2_b32 v[130:131], v175 offset0:96 offset1:97
	ds_read2_b32 v[128:129], v175 offset0:98 offset1:99
	ds_read2_b32 v[134:135], v175 offset0:80 offset1:81
	ds_read2_b32 v[132:133], v175 offset0:82 offset1:83
	ds_read2_b32 v[138:139], v175 offset0:64 offset1:65
	ds_read2_b32 v[136:137], v175 offset0:66 offset1:67
	ds_read2_b32 v[142:143], v175 offset0:48 offset1:49
	ds_read2_b32 v[140:141], v175 offset0:50 offset1:51
	ds_read2_b32 v[146:147], v175 offset0:32 offset1:33
	ds_read2_b32 v[144:145], v175 offset0:34 offset1:35
	ds_read2_b32 v[150:151], v175 offset0:16 offset1:17
	ds_read2_b32 v[148:149], v175 offset0:18 offset1:19
	ds_read2_b32 v[154:155], v175 offset0:0 offset1:1
	ds_read2_b32 v[152:153], v175 offset0:2 offset1:3
	s_waitcnt lgkmcnt(0)
	s_nop 4
	v_fma_f32 v32, v32, s50, v121
	v_fma_f32 v33, v33, s50, v120
	v_fma_f32 v34, v34, s50, v123
	v_fma_f32 v35, v35, s50, v122
	v_fma_f32 v36, v36, s50, v125
	v_fma_f32 v37, v37, s50, v124
	v_fma_f32 v38, v38, s50, v127
	v_fma_f32 v39, v39, s50, v126
	v_fma_f32 v40, v40, s50, v129
	v_fma_f32 v41, v41, s50, v128
	v_fma_f32 v42, v42, s50, v131
	v_fma_f32 v43, v43, s50, v130
	v_fma_f32 v44, v44, s50, v133
	v_fma_f32 v45, v45, s50, v132
	v_fma_f32 v46, v46, s50, v135
	v_fma_f32 v47, v47, s50, v134
	v_fma_f32 v48, v48, s50, v137
	v_fma_f32 v49, v49, s50, v136
	v_fma_f32 v50, v50, s50, v139
	v_fma_f32 v51, v51, s50, v138
	v_fma_f32 v52, v52, s50, v141
	v_fma_f32 v53, v53, s50, v140
	v_fma_f32 v54, v54, s50, v143
	v_fma_f32 v55, v55, s50, v142
	v_fma_f32 v56, v56, s50, v145
	v_fma_f32 v57, v57, s50, v144
	v_fma_f32 v58, v58, s50, v147
	v_fma_f32 v59, v59, s50, v146
	v_fma_f32 v60, v60, s50, v149
	v_fma_f32 v61, v61, s50, v148
	v_fma_f32 v62, v62, s50, v151
	v_fma_f32 v63, v63, s50, v150
	v_fma_f32 v64, v64, s50, v153
	v_fma_f32 v65, v65, s50, v152
	v_fma_f32 v66, v66, s50, v155
	v_fma_f32 v67, v67, s50, v154
	v_mov_b32_e32 v176, 0xff800000
	v_cndmask_b32_e64 v32, v32, v176, s[40:41]
	v_cndmask_b32_e64 v64, v176, v64, s[40:41]
	v_cndmask_b32_e64 v33, v33, v176, s[42:43]
	v_cndmask_b32_e64 v65, v176, v65, s[42:43]
	v_cndmask_b32_e64 v34, v34, v176, s[44:45]
	v_cndmask_b32_e64 v66, v176, v66, s[44:45]
	v_cndmask_b32_e64 v35, v35, v176, s[46:47]
	v_cndmask_b32_e64 v67, v176, v67, s[46:47]
	s_cmp_lt_u32 0, s29
	s_cbranch_scc0 .Lm1b_h3_nomask
	v_mov_b32_e32 v32, 0xff800000
	v_mov_b32_e32 v33, 0xff800000
	v_mov_b32_e32 v34, 0xff800000
	v_mov_b32_e32 v35, 0xff800000
	s_cmp_lt_u32 1, s29
	s_cbranch_scc0 .Lm1b_h3_nomask
	v_mov_b32_e32 v36, 0xff800000
	v_mov_b32_e32 v37, 0xff800000
	v_mov_b32_e32 v38, 0xff800000
	v_mov_b32_e32 v39, 0xff800000
	s_cmp_lt_u32 2, s29
	s_cbranch_scc0 .Lm1b_h3_nomask
	v_mov_b32_e32 v40, 0xff800000
	v_mov_b32_e32 v41, 0xff800000
	v_mov_b32_e32 v42, 0xff800000
	v_mov_b32_e32 v43, 0xff800000
	s_cmp_lt_u32 3, s29
	s_cbranch_scc0 .Lm1b_h3_nomask
	v_mov_b32_e32 v44, 0xff800000
	v_mov_b32_e32 v45, 0xff800000
	v_mov_b32_e32 v46, 0xff800000
	v_mov_b32_e32 v47, 0xff800000
	s_cmp_lt_u32 4, s29
	s_cbranch_scc0 .Lm1b_h3_nomask
	v_mov_b32_e32 v48, 0xff800000
	v_mov_b32_e32 v49, 0xff800000
	v_mov_b32_e32 v50, 0xff800000
	v_mov_b32_e32 v51, 0xff800000
	s_cmp_lt_u32 5, s29
	s_cbranch_scc0 .Lm1b_h3_nomask
	v_mov_b32_e32 v52, 0xff800000
	v_mov_b32_e32 v53, 0xff800000
	v_mov_b32_e32 v54, 0xff800000
	v_mov_b32_e32 v55, 0xff800000
	s_cmp_lt_u32 6, s29
	s_cbranch_scc0 .Lm1b_h3_nomask
	v_mov_b32_e32 v56, 0xff800000
	v_mov_b32_e32 v57, 0xff800000
	v_mov_b32_e32 v58, 0xff800000
	v_mov_b32_e32 v59, 0xff800000
	s_cmp_lt_u32 7, s29
	s_cbranch_scc0 .Lm1b_h3_nomask
	v_mov_b32_e32 v60, 0xff800000
	v_mov_b32_e32 v61, 0xff800000
	v_mov_b32_e32 v62, 0xff800000
	v_mov_b32_e32 v63, 0xff800000
; #define LAS __attribute__((address_space(3)))
; DI unsigned short f2bf(float f) { return (unsigned short)(pk2(f, 0.f) & 0xffffu); }
; DI float sum16(float v) { v += __shfl_xor(v, 1); v += __shfl_xor(v, 2); v += __shfl_xor(v, 4); v += __shfl_xor(v, 8); return v; }
; DI float max16(float v) { v = fmaxf(v, __shfl_xor(v, 1)); v = fmaxf(v, __shfl_xor(v, 2)); v = fmaxf(v, __shfl_xor(v, 4)); v = fmaxf(v, __shfl_xor(v, 8)); return v; }
; __global__ void __launch_bounds__(512, 2) fwd_megakernel(Args args) {
;     ...
;                         float sm[4];
; #pragma unroll
;                         for (int j = 0; j < 4; ++j) {
;                             const int i = 16 * wave + q4 * 4 + j; float m = -INFINITY;
; #pragma unroll
;                             for (int kk = 0; kk < 9; ++kk) {
;                                 const int jk = 16 * (wave + kk) + r16, dist = i - jk + 128;
;                                 const bool ok = (dist >= 0) && (dist < 128) && (nb > 0 || jk >= 128);
;                                 const float sv = ok ? sc[kk][j] * 0.125f + s_bias[hq * 128 + (dist & 127)] : -INFINITY;
;                                 sc[kk][j] = sv; m = fmaxf(m, sv);
;                             }
;                             m = fmaxf(max16(m), sink);
;                             float su = 0.f;
; #pragma unroll
;                             for (int kk = 0; kk < 9; ++kk) { const float p = __expf(sc[kk][j] - m); sc[kk][j] = p; su += p; }
;                             sm[j] = sum16(su) + __expf(sink - m);
;                         }
; #pragma unroll
;                         for (int kk = 0; kk < 9; ++kk)
; #pragma unroll
;                             for (int j = 0; j < 4; ++j) Ps[(q4 * 4 + j) * 168 + kk * 16 + r16] = f2bf(sc[kk][j]);
;                         *(LAS u32x2*)(Ps + (lane >> 2) * 168 + 144 + (lane & 3) * 4) = (u32x2){0u, 0u};
.Lm1b_h3_nomask:
	v_max3_f32 v170, v32, v33, v34
	v_max3_f32 v170, v170, v35, v36
	v_max3_f32 v170, v170, v37, v38
	v_max3_f32 v170, v170, v39, v40
	v_max3_f32 v170, v170, v41, v42
	v_max3_f32 v170, v170, v43, v44
	v_max3_f32 v170, v170, v45, v46
	v_max3_f32 v170, v170, v47, v48
	v_max3_f32 v170, v170, v49, v50
	v_max3_f32 v170, v170, v51, v52
	v_max3_f32 v170, v170, v53, v54
	v_max3_f32 v170, v170, v55, v56
	v_max3_f32 v170, v170, v57, v58
	v_max3_f32 v170, v170, v59, v60
	v_max3_f32 v170, v170, v61, v62
	v_max3_f32 v170, v170, v63, v64
	v_max3_f32 v170, v170, v65, v66
	v_max_f32_e32 v170, v170, v67
	ds_bpermute_b32 v177, v173, v170
	s_waitcnt lgkmcnt(0)
	v_max_f32_e32 v170, v170, v177
	ds_bpermute_b32 v177, v174, v170
	s_waitcnt lgkmcnt(0)
	v_max_f32_e32 v170, v170, v177
	v_max_f32_e32 v170, s39, v170
	v_mul_f32_e32 v178, 0x3fb8aa3b, v170
	v_fma_f32 v32, v32, v179, -v178
	v_fma_f32 v33, v33, v179, -v178
	v_fma_f32 v34, v34, v179, -v178
	v_fma_f32 v35, v35, v179, -v178
	v_fma_f32 v36, v36, v179, -v178
	v_fma_f32 v37, v37, v179, -v178
	v_fma_f32 v38, v38, v179, -v178
	v_fma_f32 v39, v39, v179, -v178
	v_fma_f32 v40, v40, v179, -v178
	v_fma_f32 v41, v41, v179, -v178
	v_fma_f32 v42, v42, v179, -v178
	v_fma_f32 v43, v43, v179, -v178
	v_fma_f32 v44, v44, v179, -v178
	v_fma_f32 v45, v45, v179, -v178
	v_fma_f32 v46, v46, v179, -v178
	v_fma_f32 v47, v47, v179, -v178
	v_fma_f32 v48, v48, v179, -v178
	v_fma_f32 v49, v49, v179, -v178
	v_fma_f32 v50, v50, v179, -v178
	v_fma_f32 v51, v51, v179, -v178
	v_fma_f32 v52, v52, v179, -v178
	v_fma_f32 v53, v53, v179, -v178
	v_fma_f32 v54, v54, v179, -v178
	v_fma_f32 v55, v55, v179, -v178
	v_fma_f32 v56, v56, v179, -v178
	v_fma_f32 v57, v57, v179, -v178
	v_fma_f32 v58, v58, v179, -v178
	v_fma_f32 v59, v59, v179, -v178
	v_fma_f32 v60, v60, v179, -v178
	v_fma_f32 v61, v61, v179, -v178
	v_fma_f32 v62, v62, v179, -v178
	v_fma_f32 v63, v63, v179, -v178
	v_fma_f32 v64, v64, v179, -v178
	v_fma_f32 v65, v65, v179, -v178
	v_fma_f32 v66, v66, v179, -v178
	v_fma_f32 v67, v67, v179, -v178
	v_exp_f32_e32 v32, v32
	v_exp_f32_e32 v33, v33
	v_exp_f32_e32 v34, v34
	v_exp_f32_e32 v35, v35
	v_exp_f32_e32 v36, v36
	v_exp_f32_e32 v37, v37
	v_exp_f32_e32 v38, v38
	v_exp_f32_e32 v39, v39
	v_exp_f32_e32 v40, v40
	v_exp_f32_e32 v41, v41
	v_exp_f32_e32 v42, v42
	v_exp_f32_e32 v43, v43
	v_exp_f32_e32 v44, v44
	v_exp_f32_e32 v45, v45
	v_exp_f32_e32 v46, v46
	v_exp_f32_e32 v47, v47
	v_exp_f32_e32 v48, v48
	v_exp_f32_e32 v49, v49
	v_exp_f32_e32 v50, v50
	v_exp_f32_e32 v51, v51
	v_exp_f32_e32 v52, v52
	v_exp_f32_e32 v53, v53
	v_exp_f32_e32 v54, v54
	v_exp_f32_e32 v55, v55
	v_exp_f32_e32 v56, v56
	v_exp_f32_e32 v57, v57
	v_exp_f32_e32 v58, v58
	v_exp_f32_e32 v59, v59
	v_exp_f32_e32 v60, v60
	v_exp_f32_e32 v61, v61
	v_exp_f32_e32 v62, v62
	v_exp_f32_e32 v63, v63
	v_exp_f32_e32 v64, v64
	v_exp_f32_e32 v65, v65
	v_exp_f32_e32 v66, v66
	v_exp_f32_e32 v67, v67
	s_nop 0
	v_add_f32_e32 v180, v32, v36
	v_add_f32_e32 v181, v33, v37
	v_add_f32_e32 v182, v34, v38
	v_add_f32_e32 v183, v35, v39
	v_add_f32_e32 v180, v180, v40
	v_add_f32_e32 v181, v181, v41
	v_add_f32_e32 v182, v182, v42
	v_add_f32_e32 v183, v183, v43
	v_add_f32_e32 v180, v180, v44
	v_add_f32_e32 v181, v181, v45
	v_add_f32_e32 v182, v182, v46
	v_add_f32_e32 v183, v183, v47
	v_add_f32_e32 v180, v180, v48
	v_add_f32_e32 v181, v181, v49
	v_add_f32_e32 v182, v182, v50
	v_add_f32_e32 v183, v183, v51
	v_add_f32_e32 v180, v180, v52
	v_add_f32_e32 v181, v181, v53
	v_add_f32_e32 v182, v182, v54
	v_add_f32_e32 v183, v183, v55
	v_add_f32_e32 v180, v180, v56
	v_add_f32_e32 v181, v181, v57
	v_add_f32_e32 v182, v182, v58
	v_add_f32_e32 v183, v183, v59
	v_add_f32_e32 v180, v180, v60
	v_add_f32_e32 v181, v181, v61
	v_add_f32_e32 v182, v182, v62
	v_add_f32_e32 v183, v183, v63
	v_add_f32_e32 v180, v180, v64
	v_add_f32_e32 v181, v181, v65
	v_add_f32_e32 v182, v182, v66
	v_add_f32_e32 v183, v183, v67
	v_add_f32_e32 v180, v180, v181
	v_add_f32_e32 v182, v182, v183
	v_add_f32_e32 v171, v180, v182
	ds_bpermute_b32 v177, v173, v171
	v_cvt_pk_bf16_f32 v84, v32, v33
	v_cvt_pk_bf16_f32 v85, v34, v35
	v_cvt_pk_bf16_f32 v86, v36, v37
	v_cvt_pk_bf16_f32 v87, v38, v39
	v_cvt_pk_bf16_f32 v88, v40, v41
	v_cvt_pk_bf16_f32 v89, v42, v43
	v_cvt_pk_bf16_f32 v90, v44, v45
	v_cvt_pk_bf16_f32 v91, v46, v47
	v_cvt_pk_bf16_f32 v92, v48, v49
	v_cvt_pk_bf16_f32 v93, v50, v51
	v_cvt_pk_bf16_f32 v94, v52, v53
	v_cvt_pk_bf16_f32 v95, v54, v55
	v_cvt_pk_bf16_f32 v96, v56, v57
	v_cvt_pk_bf16_f32 v97, v58, v59
	v_cvt_pk_bf16_f32 v98, v60, v61
	v_cvt_pk_bf16_f32 v99, v62, v63
	v_cvt_pk_bf16_f32 v100, v64, v65
	v_cvt_pk_bf16_f32 v101, v66, v67
	v_mov_b32_e32 v102, 0
	v_mov_b32_e32 v103, 0
	s_waitcnt lgkmcnt(0)
	v_add_f32_e32 v171, v171, v177
	ds_bpermute_b32 v177, v174, v171
	v_sub_f32_e32 v176, s39, v170
	v_mul_f32_e32 v176, 0x3fb8aa3b, v176
	v_exp_f32_e32 v176, v176
	ds_read_b64_tr_b16 v[120:121], v163 offset:0
	ds_read_b64_tr_b16 v[122:123], v163 offset:2304
	ds_read_b64_tr_b16 v[124:125], v163 offset:32
	ds_read_b64_tr_b16 v[126:127], v163 offset:2336
	ds_read_b64_tr_b16 v[128:129], v163 offset:64
	ds_read_b64_tr_b16 v[130:131], v163 offset:2368
	ds_read_b64_tr_b16 v[132:133], v163 offset:96
	ds_read_b64_tr_b16 v[134:135], v163 offset:2400
	s_waitcnt lgkmcnt(8)
; DI unsigned short f2bf(float f) { return (unsigned short)(pk2(f, 0.f) & 0xffffu); }
; DI float sum16(float v) { v += __shfl_xor(v, 1); v += __shfl_xor(v, 2); v += __shfl_xor(v, 4); v += __shfl_xor(v, 8); return v; }
; DI f32x4 mfma16(bf16x8 a, bf16x8 b, f32x4 c) { return __builtin_amdgcn_mfma_f32_16x16x32_bf16(a, b, c, 0, 0, 0); }
; __global__ void __launch_bounds__(512, 2) fwd_megakernel(Args args) {
;     ...
;                         f32x4 oa[4];
; #pragma unroll
;                         for (int dt = 0; dt < 4; ++dt) oa[dt] = (f32x4){0.f, 0.f, 0.f, 0.f};
; #pragma unroll
;                         for (int ks = 0; ks < 5; ++ks) {
;                             const bf16x8 pa = lds_frag(Ps, r16, 168, ks * 32 + q4 * 8);
; #pragma unroll
;                             for (int dt = 0; dt < 4; ++dt) oa[dt] = mfma16(pa, lds_frag(VT, 16 * dt + r16, 280, 16 * wave + ks * 32 + q4 * 8), oa[dt]);
;                         }
; #pragma unroll
;                         for (int j = 0; j < 4; ++j) { const float inv = 1.f / sm[j];
; #pragma unroll
;                             for (int dt = 0; dt < 4; ++dt) { const float o = oa[dt][j] * inv; ssr[j] += o * o; og[hq][dt][j] = o; } }
;                     }
;                 }
; #pragma unroll
;                 for (int hq = 0; hq < 4; ++hq) {
; #pragma unroll
;                     for (int j = 0; j < 4; ++j) {
;                         const size_t row = grow0 + 16 * wave + q4 * 4 + j; float ss = 0.f;
; #pragma unroll
;                         for (int dt = 0; dt < 4; ++dt) { const float o = og[hq][dt][j]; ss += o * o; Yg[row * DM + 512 + hq * 64 + 16 * dt + r16] = f2bf(o); }
;                         ss = sum16(ss);
;                         if (r16 == 0) mss_a[(size_t)hq * MTOK + row] = ss;
;                     }
;                 }
	v_add_f32_e32 v171, v171, v177
	v_add_f32_e32 v171, v171, v176
	s_waitcnt lgkmcnt(0)
	ds_read_b64_tr_b16 v[136:137], v163 offset:4608
	ds_read_b64_tr_b16 v[138:139], v163 offset:6912
	ds_read_b64_tr_b16 v[140:141], v163 offset:4640
	ds_read_b64_tr_b16 v[142:143], v163 offset:6944
	ds_read_b64_tr_b16 v[144:145], v163 offset:4672
	ds_read_b64_tr_b16 v[146:147], v163 offset:6976
	ds_read_b64_tr_b16 v[148:149], v163 offset:4704
	ds_read_b64_tr_b16 v[150:151], v163 offset:7008
	v_mfma_f32_16x16x32_bf16 v[68:71], v[120:123], v[84:87], 0
	v_mfma_f32_16x16x32_bf16 v[72:75], v[124:127], v[84:87], 0
	v_mfma_f32_16x16x32_bf16 v[76:79], v[128:131], v[84:87], 0
	v_mfma_f32_16x16x32_bf16 v[80:83], v[132:135], v[84:87], 0
	s_waitcnt lgkmcnt(0)
	ds_read_b64_tr_b16 v[120:121], v163 offset:9216
	ds_read_b64_tr_b16 v[122:123], v163 offset:11520
	ds_read_b64_tr_b16 v[124:125], v163 offset:9248
	ds_read_b64_tr_b16 v[126:127], v163 offset:11552
	ds_read_b64_tr_b16 v[128:129], v163 offset:9280
	ds_read_b64_tr_b16 v[130:131], v163 offset:11584
	ds_read_b64_tr_b16 v[132:133], v163 offset:9312
	ds_read_b64_tr_b16 v[134:135], v163 offset:11616
	v_mfma_f32_16x16x32_bf16 v[68:71], v[136:139], v[88:91], v[68:71]
	v_mfma_f32_16x16x32_bf16 v[72:75], v[140:143], v[88:91], v[72:75]
	v_mfma_f32_16x16x32_bf16 v[76:79], v[144:147], v[88:91], v[76:79]
	v_mfma_f32_16x16x32_bf16 v[80:83], v[148:151], v[88:91], v[80:83]
	s_waitcnt lgkmcnt(0)
	ds_read_b64_tr_b16 v[136:137], v163 offset:13824
	ds_read_b64_tr_b16 v[138:139], v163 offset:16128
	ds_read_b64_tr_b16 v[140:141], v163 offset:13856
	ds_read_b64_tr_b16 v[142:143], v163 offset:16160
	ds_read_b64_tr_b16 v[144:145], v163 offset:13888
	ds_read_b64_tr_b16 v[146:147], v163 offset:16192
	ds_read_b64_tr_b16 v[148:149], v163 offset:13920
	ds_read_b64_tr_b16 v[150:151], v163 offset:16224
	v_mfma_f32_16x16x32_bf16 v[68:71], v[120:123], v[92:95], v[68:71]
	v_mfma_f32_16x16x32_bf16 v[72:75], v[124:127], v[92:95], v[72:75]
	v_mfma_f32_16x16x32_bf16 v[76:79], v[128:131], v[92:95], v[76:79]
	v_mfma_f32_16x16x32_bf16 v[80:83], v[132:135], v[92:95], v[80:83]
	s_waitcnt lgkmcnt(0)
	ds_read_b64_tr_b16 v[120:121], v163 offset:18432
	ds_read_b64_tr_b16 v[122:123], v163 offset:20736
	ds_read_b64_tr_b16 v[124:125], v163 offset:18464
	ds_read_b64_tr_b16 v[126:127], v163 offset:20768
	ds_read_b64_tr_b16 v[128:129], v163 offset:18496
	ds_read_b64_tr_b16 v[130:131], v163 offset:20800
	ds_read_b64_tr_b16 v[132:133], v163 offset:18528
	ds_read_b64_tr_b16 v[134:135], v163 offset:20832
	v_mfma_f32_16x16x32_bf16 v[68:71], v[136:139], v[96:99], v[68:71]
	v_mfma_f32_16x16x32_bf16 v[72:75], v[140:143], v[96:99], v[72:75]
	v_mfma_f32_16x16x32_bf16 v[76:79], v[144:147], v[96:99], v[76:79]
	v_mfma_f32_16x16x32_bf16 v[80:83], v[148:151], v[96:99], v[80:83]
	s_waitcnt lgkmcnt(0)
	v_mfma_f32_16x16x32_bf16 v[68:71], v[120:123], v[100:103], v[68:71]
	v_mfma_f32_16x16x32_bf16 v[72:75], v[124:127], v[100:103], v[72:75]
	v_mfma_f32_16x16x32_bf16 v[76:79], v[128:131], v[100:103], v[76:79]
	v_mfma_f32_16x16x32_bf16 v[80:83], v[132:135], v[100:103], v[80:83]
	v_rcp_f32_e32 v172, v171
	s_nop 7
	s_nop 3
	v_mul_f32_e32 v68, v68, v172
	v_mul_f32_e32 v69, v69, v172
	v_mul_f32_e32 v70, v70, v172
	v_mul_f32_e32 v71, v71, v172
	v_mul_f32_e32 v171, v68, v68
	v_fmac_f32_e32 v171, v69, v69
	v_fmac_f32_e32 v171, v70, v70
	v_fmac_f32_e32 v171, v71, v71
	v_cvt_pk_bf16_f32 v180, v68, v69
	v_cvt_pk_bf16_f32 v181, v70, v71
	global_store_dwordx2 v165, v[180:181], s[10:11] offset:384
	v_mul_f32_e32 v72, v72, v172
	v_mul_f32_e32 v73, v73, v172
	v_mul_f32_e32 v74, v74, v172
	v_mul_f32_e32 v75, v75, v172
	v_fmac_f32_e32 v171, v72, v72
	v_fmac_f32_e32 v171, v73, v73
	v_fmac_f32_e32 v171, v74, v74
	v_fmac_f32_e32 v171, v75, v75
	v_cvt_pk_bf16_f32 v180, v72, v73
	v_cvt_pk_bf16_f32 v181, v74, v75
	global_store_dwordx2 v165, v[180:181], s[10:11] offset:416
	v_mul_f32_e32 v76, v76, v172
	v_mul_f32_e32 v77, v77, v172
	v_mul_f32_e32 v78, v78, v172
	v_mul_f32_e32 v79, v79, v172
	v_fmac_f32_e32 v171, v76, v76
	v_fmac_f32_e32 v171, v77, v77
	v_fmac_f32_e32 v171, v78, v78
	v_fmac_f32_e32 v171, v79, v79
	v_cvt_pk_bf16_f32 v180, v76, v77
	v_cvt_pk_bf16_f32 v181, v78, v79
	global_store_dwordx2 v165, v[180:181], s[10:11] offset:448
	v_mul_f32_e32 v80, v80, v172
	v_mul_f32_e32 v81, v81, v172
	v_mul_f32_e32 v82, v82, v172
	v_mul_f32_e32 v83, v83, v172
	v_fmac_f32_e32 v171, v80, v80
	v_fmac_f32_e32 v171, v81, v81
	v_fmac_f32_e32 v171, v82, v82
	v_fmac_f32_e32 v171, v83, v83
	v_cvt_pk_bf16_f32 v180, v80, v81
	v_cvt_pk_bf16_f32 v181, v82, v83
	global_store_dwordx2 v165, v[180:181], s[10:11] offset:480
	ds_bpermute_b32 v177, v173, v171
	s_waitcnt lgkmcnt(0)
	v_add_f32_e32 v171, v171, v177
	ds_bpermute_b32 v177, v174, v171
	s_waitcnt lgkmcnt(0)
	v_add_f32_e32 v171, v171, v177
	s_mov_b64 exec, s[48:49]
	global_store_dword v166, v171, s[30:31]
	s_mov_b64 exec, -1
	v_xor_b32_e32 v88, 1, v228
	v_lshlrev_b32_e32 v88, 2, v88
	v_xor_b32_e32 v89, 2, v228
	v_lshlrev_b32_e32 v89, 2, v89
	v_xor_b32_e32 v90, 4, v228
	v_lshlrev_b32_e32 v90, 2, v90
	v_xor_b32_e32 v91, 8, v228
	v_lshlrev_b32_e32 v91, 2, v91
	s_mov_b64 s[6:7], -1
	s_branch .LBB0_447

; __global__ void __launch_bounds__(512, 2) fwd_megakernel(Args args) {
;     ...
;                         bf16x8 pvf[4][4];
;                         {
;                             const bf16* pv = PV + (size_t)unit8 * 8192;
; #pragma unroll
;                             for (int ks = 0; ks < 4; ++ks)
; #pragma unroll
;                                 for (int pt = 0; pt < 4; ++pt) pvf[ks][pt] = *(const bf16x8*)(pv + (16 * pt + r16) * 128 + ks * 32 + q4 * 8);
;                         }
;                         bf16 zr[4][4];
; #pragma unroll
;                         for (int j = 0; j < 4; ++j)
; #pragma unroll
;                             for (int pt = 0; pt < 4; ++pt) zr[j][pt] = proj[(grow0 + 16 * wave + q4 * 4 + j) * NPROJ + PC_Z + h * 64 + 16 * pt + r16];
;                         const LAS float* hdt = s_dt + hh * 128; const LAS float* hacs = s_acs + hh * 128;
;                         float acl[4];
; #pragma unroll
;                         for (int j = 0; j < 4; ++j) acl[j] = hacs[16 * wave + q4 * 4 + j];
; #pragma unroll
;                         for (int st = 0; st < 8; ++st) {
;                             if (st <= (wave | 1)) {
;                                 const int sI = 16 * st + r16; const float acss = hacs[sI], dts = hdt[sI];
; #pragma unroll
;                                 for (int j = 0; j < 4; ++j) { const int l = 16 * wave + q4 * 4 + j; const float mv = (sI <= l) ? cbr[st][j] * __expf(fminf(acl[j] - acss, 0.f)) * dts : 0.f; Ms[l * 136 + sI] = f2bf(mv); }
;                             }
;                         }
;                         f32x4 yo[4], yd[4];
; #pragma unroll
;                         for (int pt = 0; pt < 4; ++pt) { yo[pt] = (f32x4){0.f, 0.f, 0.f, 0.f}; yd[pt] = (f32x4){0.f, 0.f, 0.f, 0.f}; }
;                         const LAS bf16* xh = xT + hh * (64 * 136);
; #pragma unroll
;                         for (int ks = 0; ks < 4; ++ks) {
;                             if (2 * ks <= wave) {
;                                 const bf16x8 ma = lds_frag(Ms, lrow, 136, ks * 32 + q4 * 8);
; #pragma unroll
;                                 for (int pt = 0; pt < 4; ++pt) yd[pt] = mfma16(ma, lds_frag(xh, 16 * pt + r16, 136, ks * 32 + q4 * 8), yd[pt]);
;                             }
;                         }
; #pragma unroll
;                         for (int ks = 0; ks < 4; ++ks)
; #pragma unroll
.Lm3_msdone_m0:
	v_mul_f32_e32 v207, 0x3fb8aa3b, v206
	v_exp_f32_e32 v207, v207
	ds_read_u16 v136, v191 offset:0
	ds_read_u16 v137, v191 offset:272
	ds_read_u16 v138, v191 offset:544
	ds_read_u16 v139, v191 offset:816
	ds_read_u16 v140, v191 offset:4352
	ds_read_u16 v141, v191 offset:4624
	ds_read_u16 v142, v191 offset:4896
	ds_read_u16 v143, v191 offset:5168
	ds_read_u16 v144, v191 offset:8704
	ds_read_u16 v145, v191 offset:8976
	ds_read_u16 v146, v191 offset:9248
	ds_read_u16 v147, v191 offset:9520
	ds_read_u16 v148, v191 offset:13056
	ds_read_u16 v149, v191 offset:13328
	ds_read_u16 v150, v191 offset:13600
	ds_read_u16 v151, v191 offset:13872
	s_waitcnt lgkmcnt(0)
	s_barrier
	v_add_u32_e32 v180, s28, v178
	ds_read_b128 v[48:51], v180 offset:0
	ds_read_b128 v[52:55], v180 offset:4352
	ds_read_b128 v[56:59], v180 offset:8704
	ds_read_b128 v[60:63], v180 offset:13056
	ds_read_b128 v[64:67], v180 offset:64
	ds_read_b128 v[68:71], v180 offset:4416
	ds_read_b128 v[72:75], v180 offset:8768
	ds_read_b128 v[76:79], v180 offset:13120
	ds_read_b128 v[80:83], v180 offset:128
	ds_read_b128 v[84:87], v180 offset:4480
	ds_read_b128 v[88:91], v180 offset:8832
	ds_read_b128 v[92:95], v180 offset:13184
	ds_read_b128 v[96:99], v180 offset:192
	ds_read_b128 v[100:103], v180 offset:4544
	ds_read_b128 v[104:107], v180 offset:8896
	ds_read_b128 v[108:111], v180 offset:13248
	s_waitcnt lgkmcnt(0)
	v_mfma_f32_16x16x32_bf16 v[112:115], v[48:51], v[32:35], 0
	v_mfma_f32_16x16x32_bf16 v[116:119], v[52:55], v[32:35], 0
	v_mfma_f32_16x16x32_bf16 v[120:123], v[56:59], v[32:35], 0
	v_mfma_f32_16x16x32_bf16 v[124:127], v[60:63], v[32:35], 0
	v_mfma_f32_16x16x32_bf16 v[112:115], v[64:67], v[36:39], v[112:115]
	v_mfma_f32_16x16x32_bf16 v[116:119], v[68:71], v[36:39], v[116:119]
	v_mfma_f32_16x16x32_bf16 v[120:123], v[72:75], v[36:39], v[120:123]
	v_mfma_f32_16x16x32_bf16 v[124:127], v[76:79], v[36:39], v[124:127]
	v_mfma_f32_16x16x32_bf16 v[112:115], v[80:83], v[40:43], v[112:115]
	v_mfma_f32_16x16x32_bf16 v[116:119], v[84:87], v[40:43], v[116:119]
	v_mfma_f32_16x16x32_bf16 v[120:123], v[88:91], v[40:43], v[120:123]
	v_mfma_f32_16x16x32_bf16 v[124:127], v[92:95], v[40:43], v[124:127]
	v_mfma_f32_16x16x32_bf16 v[112:115], v[96:99], v[44:47], v[112:115]
	v_mfma_f32_16x16x32_bf16 v[116:119], v[100:103], v[44:47], v[116:119]
	v_mfma_f32_16x16x32_bf16 v[120:123], v[104:107], v[44:47], v[120:123]
	v_mfma_f32_16x16x32_bf16 v[124:127], v[108:111], v[44:47], v[124:127]
	s_nop 7
	s_nop 3
	v_mul_f32_e32 v112, v207, v112
	v_mul_f32_e32 v113, v207, v113
	v_mul_f32_e32 v114, v207, v114
	v_mul_f32_e32 v115, v207, v115
	v_mul_f32_e32 v116, v207, v116
	v_mul_f32_e32 v117, v207, v117
	v_mul_f32_e32 v118, v207, v118
	v_mul_f32_e32 v119, v207, v119
	v_mul_f32_e32 v120, v207, v120
	v_mul_f32_e32 v121, v207, v121
	v_mul_f32_e32 v122, v207, v122
	v_mul_f32_e32 v123, v207, v123
	v_mul_f32_e32 v124, v207, v124
	v_mul_f32_e32 v125, v207, v125
	v_mul_f32_e32 v126, v207, v126
	v_mul_f32_e32 v127, v207, v127
	ds_read_b128 v[160:163], v179 offset:34816
	ds_read_b128 v[164:167], v190 offset:0
	ds_read_b128 v[168:171], v190 offset:4352
	ds_read_b128 v[172:175], v190 offset:8704
	ds_read_b128 v[152:155], v190 offset:13056
	s_waitcnt lgkmcnt(0)
	v_mfma_f32_16x16x32_bf16 v[112:115], v[164:167], v[160:163], v[112:115]
	v_mfma_f32_16x16x32_bf16 v[116:119], v[168:171], v[160:163], v[116:119]
	v_mfma_f32_16x16x32_bf16 v[120:123], v[172:175], v[160:163], v[120:123]
	v_mfma_f32_16x16x32_bf16 v[124:127], v[152:155], v[160:163], v[124:127]
	s_cmp_lt_u32 s2, 2
	s_cbranch_scc1 .Lm3_yddone_y0
	ds_read_b128 v[160:163], v179 offset:34880
	ds_read_b128 v[164:167], v190 offset:64
	ds_read_b128 v[168:171], v190 offset:4416
	ds_read_b128 v[172:175], v190 offset:8768
	ds_read_b128 v[152:155], v190 offset:13120
	s_waitcnt lgkmcnt(0)
	v_mfma_f32_16x16x32_bf16 v[112:115], v[164:167], v[160:163], v[112:115]
	v_mfma_f32_16x16x32_bf16 v[116:119], v[168:171], v[160:163], v[116:119]
	v_mfma_f32_16x16x32_bf16 v[120:123], v[172:175], v[160:163], v[120:123]
	v_mfma_f32_16x16x32_bf16 v[124:127], v[152:155], v[160:163], v[124:127]
	s_cmp_lt_u32 s2, 4
	s_cbranch_scc1 .Lm3_yddone_y0
	ds_read_b128 v[160:163], v179 offset:34944
	ds_read_b128 v[164:167], v190 offset:128
	ds_read_b128 v[168:171], v190 offset:4480
	ds_read_b128 v[172:175], v190 offset:8832
	ds_read_b128 v[152:155], v190 offset:13184
	s_waitcnt lgkmcnt(0)
	v_mfma_f32_16x16x32_bf16 v[112:115], v[164:167], v[160:163], v[112:115]
	v_mfma_f32_16x16x32_bf16 v[116:119], v[168:171], v[160:163], v[116:119]
	v_mfma_f32_16x16x32_bf16 v[120:123], v[172:175], v[160:163], v[120:123]
	v_mfma_f32_16x16x32_bf16 v[124:127], v[152:155], v[160:163], v[124:127]
	s_cmp_lt_u32 s2, 6
	s_cbranch_scc1 .Lm3_yddone_y0
	ds_read_b128 v[160:163], v179 offset:35008
	ds_read_b128 v[164:167], v190 offset:192
	ds_read_b128 v[168:171], v190 offset:4544
	ds_read_b128 v[172:175], v190 offset:8896
	ds_read_b128 v[152:155], v190 offset:13248
	s_waitcnt lgkmcnt(0)
	v_mfma_f32_16x16x32_bf16 v[112:115], v[164:167], v[160:163], v[112:115]
	v_mfma_f32_16x16x32_bf16 v[116:119], v[168:171], v[160:163], v[116:119]
	v_mfma_f32_16x16x32_bf16 v[120:123], v[172:175], v[160:163], v[120:123]
	v_mfma_f32_16x16x32_bf16 v[124:127], v[152:155], v[160:163], v[124:127]

; DI float bf2f(unsigned short b) { return __uint_as_float((unsigned)b << 16); }
; DI unsigned short f2bf(float f) { return (unsigned short)(pk2(f, 0.f) & 0xffffu); }
; DI float silu_f(float x) { return x * fast_sigmoid(x); }
; DI float sum16(float v) { v += __shfl_xor(v, 1); v += __shfl_xor(v, 2); v += __shfl_xor(v, 4); v += __shfl_xor(v, 8); return v; }
; __global__ void __launch_bounds__(512, 2) fwd_megakernel(Args args) {
;     ...
;                         const float Dh = args.in[11][layer * 8 + h];
; #pragma unroll
;                         for (int j = 0; j < 4; ++j) {
;                             const int l = 16 * wave + q4 * 4 + j; const size_t row = grow0 + l; const float ea = __expf(acl[j]); float ss = 0.f;
; #pragma unroll
;                             for (int pt = 0; pt < 4; ++pt) {
;                                 const int p = 16 * pt + r16;
;                                 const float y = yd[pt][j] + ea * yo[pt][j] + Dh * bf2f(xh[p * 136 + l]);
;                                 const float o = y * silu_f(bf2f(zr[j][pt])); ss += o * o; Yg[row * DM + h * 64 + p] = f2bf(o);
;                             }
;                             ss = sum16(ss);
;                             if (r16 == 0) mss_g[((size_t)g2 * MTOK + row) * 4 + hh] = ss;
;                         }
.Lm3_nost:
	s_nop 7
	s_nop 3
	v_lshlrev_b32_e32 v160, 16, v128
	v_and_b32_e32 v161, 0xffff0000, v128
	v_lshlrev_b32_e32 v162, 16, v129
	v_and_b32_e32 v163, 0xffff0000, v129
	v_lshlrev_b32_e32 v168, 16, v136
	v_lshlrev_b32_e32 v169, 16, v137
	v_lshlrev_b32_e32 v170, 16, v138
	v_lshlrev_b32_e32 v171, 16, v139
	v_fma_f32 v168, s36, v168, v112
	v_fma_f32 v169, s36, v169, v113
	v_fma_f32 v170, s36, v170, v114
	v_fma_f32 v171, s36, v171, v115
	v_mul_f32_e32 v164, 0xbfb8aa3b, v160
	v_mul_f32_e32 v165, 0xbfb8aa3b, v161
	v_mul_f32_e32 v166, 0xbfb8aa3b, v162
	v_mul_f32_e32 v167, 0xbfb8aa3b, v163
	v_exp_f32_e32 v164, v164
	v_exp_f32_e32 v165, v165
	v_exp_f32_e32 v166, v166
	v_exp_f32_e32 v167, v167
	s_nop 0
	v_add_f32_e32 v164, 1.0, v164
	v_add_f32_e32 v165, 1.0, v165
	v_add_f32_e32 v166, 1.0, v166
	v_add_f32_e32 v167, 1.0, v167
	v_rcp_f32_e32 v164, v164
	v_rcp_f32_e32 v165, v165
	v_rcp_f32_e32 v166, v166
	v_rcp_f32_e32 v167, v167
	s_nop 0
	v_mul_f32_e32 v164, v164, v160
	v_mul_f32_e32 v165, v165, v161
	v_mul_f32_e32 v166, v166, v162
	v_mul_f32_e32 v167, v167, v163
	v_mul_f32_e32 v164, v168, v164
	v_mul_f32_e32 v165, v169, v165
	v_mul_f32_e32 v166, v170, v166
	v_mul_f32_e32 v167, v171, v167
	v_mul_f32_e32 v208, v164, v164
	v_fmac_f32_e32 v208, v165, v165
	v_fmac_f32_e32 v208, v166, v166
	v_fmac_f32_e32 v208, v167, v167
	v_cvt_pk_bf16_f32 v172, v164, v165
	v_cvt_pk_bf16_f32 v173, v166, v167
	global_store_dwordx2 v185, v[172:173], s[12:13] offset:0
	v_lshlrev_b32_e32 v160, 16, v130
	v_and_b32_e32 v161, 0xffff0000, v130
	v_lshlrev_b32_e32 v162, 16, v131
	v_and_b32_e32 v163, 0xffff0000, v131
	v_lshlrev_b32_e32 v168, 16, v140
	v_lshlrev_b32_e32 v169, 16, v141
	v_lshlrev_b32_e32 v170, 16, v142
	v_lshlrev_b32_e32 v171, 16, v143
	v_fma_f32 v168, s36, v168, v116
	v_fma_f32 v169, s36, v169, v117
	v_fma_f32 v170, s36, v170, v118
	v_fma_f32 v171, s36, v171, v119
	v_mul_f32_e32 v164, 0xbfb8aa3b, v160
	v_mul_f32_e32 v165, 0xbfb8aa3b, v161
	v_mul_f32_e32 v166, 0xbfb8aa3b, v162
	v_mul_f32_e32 v167, 0xbfb8aa3b, v163
	v_exp_f32_e32 v164, v164
	v_exp_f32_e32 v165, v165
	v_exp_f32_e32 v166, v166
	v_exp_f32_e32 v167, v167
	s_nop 0
	v_add_f32_e32 v164, 1.0, v164
	v_add_f32_e32 v165, 1.0, v165
	v_add_f32_e32 v166, 1.0, v166
	v_add_f32_e32 v167, 1.0, v167
	v_rcp_f32_e32 v164, v164
	v_rcp_f32_e32 v165, v165
	v_rcp_f32_e32 v166, v166
	v_rcp_f32_e32 v167, v167
	s_nop 0
	v_mul_f32_e32 v164, v164, v160
	v_mul_f32_e32 v165, v165, v161
	v_mul_f32_e32 v166, v166, v162
	v_mul_f32_e32 v167, v167, v163
	v_mul_f32_e32 v164, v168, v164
	v_mul_f32_e32 v165, v169, v165
	v_mul_f32_e32 v166, v170, v166
	v_mul_f32_e32 v167, v171, v167
	v_fmac_f32_e32 v208, v164, v164
	v_fmac_f32_e32 v208, v165, v165
	v_fmac_f32_e32 v208, v166, v166
	v_fmac_f32_e32 v208, v167, v167
	v_cvt_pk_bf16_f32 v172, v164, v165
	v_cvt_pk_bf16_f32 v173, v166, v167
	global_store_dwordx2 v185, v[172:173], s[12:13] offset:32
	v_lshlrev_b32_e32 v160, 16, v132
	v_and_b32_e32 v161, 0xffff0000, v132
	v_lshlrev_b32_e32 v162, 16, v133
	v_and_b32_e32 v163, 0xffff0000, v133
	v_lshlrev_b32_e32 v168, 16, v144
	v_lshlrev_b32_e32 v169, 16, v145
	v_lshlrev_b32_e32 v170, 16, v146
	v_lshlrev_b32_e32 v171, 16, v147
	v_fma_f32 v168, s36, v168, v120
	v_fma_f32 v169, s36, v169, v121
	v_fma_f32 v170, s36, v170, v122
	v_fma_f32 v171, s36, v171, v123
	v_mul_f32_e32 v164, 0xbfb8aa3b, v160
	v_mul_f32_e32 v165, 0xbfb8aa3b, v161
	v_mul_f32_e32 v166, 0xbfb8aa3b, v162
	v_mul_f32_e32 v167, 0xbfb8aa3b, v163
	v_exp_f32_e32 v164, v164
	v_exp_f32_e32 v165, v165
	v_exp_f32_e32 v166, v166
	v_exp_f32_e32 v167, v167
	s_nop 0
	v_add_f32_e32 v164, 1.0, v164
	v_add_f32_e32 v165, 1.0, v165
	v_add_f32_e32 v166, 1.0, v166
	v_add_f32_e32 v167, 1.0, v167
	v_rcp_f32_e32 v164, v164
	v_rcp_f32_e32 v165, v165
	v_rcp_f32_e32 v166, v166
	v_rcp_f32_e32 v167, v167
	s_nop 0
	v_mul_f32_e32 v164, v164, v160
	v_mul_f32_e32 v165, v165, v161
	v_mul_f32_e32 v166, v166, v162
	v_mul_f32_e32 v167, v167, v163
	v_mul_f32_e32 v164, v168, v164
	v_mul_f32_e32 v165, v169, v165
	v_mul_f32_e32 v166, v170, v166
	v_mul_f32_e32 v167, v171, v167
	v_fmac_f32_e32 v208, v164, v164
	v_fmac_f32_e32 v208, v165, v165
	v_fmac_f32_e32 v208, v166, v166
	v_fmac_f32_e32 v208, v167, v167
	v_cvt_pk_bf16_f32 v172, v164, v165
	v_cvt_pk_bf16_f32 v173, v166, v167
	global_store_dwordx2 v185, v[172:173], s[12:13] offset:64
	v_lshlrev_b32_e32 v160, 16, v134
	v_and_b32_e32 v161, 0xffff0000, v134
	v_lshlrev_b32_e32 v162, 16, v135
	v_and_b32_e32 v163, 0xffff0000, v135
	v_lshlrev_b32_e32 v168, 16, v148
	v_lshlrev_b32_e32 v169, 16, v149
	v_lshlrev_b32_e32 v170, 16, v150
	v_lshlrev_b32_e32 v171, 16, v151
	v_fma_f32 v168, s36, v168, v124
	v_fma_f32 v169, s36, v169, v125
	v_fma_f32 v170, s36, v170, v126
	v_fma_f32 v171, s36, v171, v127
	v_mul_f32_e32 v164, 0xbfb8aa3b, v160
	v_mul_f32_e32 v165, 0xbfb8aa3b, v161
	v_mul_f32_e32 v166, 0xbfb8aa3b, v162
	v_mul_f32_e32 v167, 0xbfb8aa3b, v163
	v_exp_f32_e32 v164, v164
	v_exp_f32_e32 v165, v165
	v_exp_f32_e32 v166, v166
	v_exp_f32_e32 v167, v167
	s_nop 0
	v_add_f32_e32 v164, 1.0, v164
	v_add_f32_e32 v165, 1.0, v165
	v_add_f32_e32 v166, 1.0, v166
	v_add_f32_e32 v167, 1.0, v167
	v_rcp_f32_e32 v164, v164
	v_rcp_f32_e32 v165, v165
	v_rcp_f32_e32 v166, v166
	v_rcp_f32_e32 v167, v167
	s_nop 0
	v_mul_f32_e32 v164, v164, v160
	v_mul_f32_e32 v165, v165, v161
	v_mul_f32_e32 v166, v166, v162
	v_mul_f32_e32 v167, v167, v163
	v_mul_f32_e32 v164, v168, v164
	v_mul_f32_e32 v165, v169, v165
	v_mul_f32_e32 v166, v170, v166
	v_mul_f32_e32 v167, v171, v167
	v_fmac_f32_e32 v208, v164, v164
	v_fmac_f32_e32 v208, v165, v165
	v_fmac_f32_e32 v208, v166, v166
	v_fmac_f32_e32 v208, v167, v167
	v_cvt_pk_bf16_f32 v172, v164, v165
	v_cvt_pk_bf16_f32 v173, v166, v167
	global_store_dwordx2 v185, v[172:173], s[12:13] offset:96
	ds_bpermute_b32 v213, v211, v208
	s_waitcnt lgkmcnt(0)
	v_add_f32_e32 v208, v208, v213
	ds_bpermute_b32 v213, v212, v208
	s_waitcnt lgkmcnt(0)
	v_add_f32_e32 v208, v208, v213
	s_mov_b64 exec, s[42:43]
	global_store_dword v186, v208, s[22:23]
	s_mov_b64 exec, -1
	s_cmp_eq_u32 s3, 3
	s_cbranch_scc1 .Lm3_exit
	s_add_u32 s10, s10, 0x80
	s_addc_u32 s11, s11, 0
	global_load_dwordx2 v[128:129], v184, s[10:11] offset:0
	global_load_dwordx2 v[130:131], v184, s[10:11] offset:32
	global_load_dwordx2 v[132:133], v184, s[10:11] offset:64
	global_load_dwordx2 v[134:135], v184, s[10:11] offset:96
	s_add_u32 s12, s12, 0x80
	s_addc_u32 s13, s13, 0
	s_add_u32 s22, s22, 4
	s_addc_u32 s23, s23, 0
	v_add_u32_e32 v187, 0x200, v187
	v_add_u32_e32 v188, 0x200, v188
	v_add_u32_e32 v190, 0x4400, v190
	v_add_u32_e32 v191, 0x4400, v191
	s_mov_b32 s36, s37
	s_mov_b32 s37, s38
	s_mov_b32 s38, s39
	s_xor_b32 s28, s28, 0x4400
	s_add_i32 s3, s3, 1
	s_branch .Lm3_head
